# scan: lane-15 carry broadcast with DPP row_newbcast instead of ds_bpermute
# speedup vs baseline: 1.0226x; 1.0034x over previous
.Lscan1_back0:
	v_sqrt_f32_e32 v216, v216
	v_sqrt_f32_e32 v217, v217
	v_sqrt_f32_e32 v218, v218
	v_sqrt_f32_e32 v219, v219
	v_pk_mul_f32 v[204:205], v[204:205], v[216:217]
	v_pk_mul_f32 v[206:207], v[206:207], v[218:219]
	s_waitcnt lgkmcnt(0)
	v_mfma_f32_16x16x32_bf16 v[142:145], v[110:113], v[98:101], 0
	v_mfma_f32_16x16x32_bf16 v[146:149], v[122:125], v[98:101], 0
	v_mfma_f32_16x16x32_bf16 v[142:145], v[114:117], v[102:105], v[142:145]
	v_mfma_f32_16x16x32_bf16 v[146:149], v[126:129], v[102:105], v[146:149]
	v_mfma_f32_16x16x32_bf16 v[142:145], v[118:121], v[106:109], v[142:145]
	v_mfma_f32_16x16x32_bf16 v[146:149], v[130:133], v[106:109], v[146:149]
	s_nop 1
	v_fmac_f32_dpp v204, v204, v166 row_shr:1 row_mask:0xf bank_mask:0xf bound_ctrl:1
	v_fmac_f32_dpp v205, v205, v167 row_shr:1 row_mask:0xf bank_mask:0xf bound_ctrl:1
	v_fmac_f32_dpp v206, v206, v168 row_shr:1 row_mask:0xf bank_mask:0xf bound_ctrl:1
	v_fmac_f32_dpp v207, v207, v169 row_shr:1 row_mask:0xf bank_mask:0xf bound_ctrl:1
	v_mul_f32_dpp v166, v166, v166 row_shr:1 row_mask:0xf bank_mask:0xf
	v_mul_f32_dpp v167, v167, v167 row_shr:1 row_mask:0xf bank_mask:0xf
	v_mul_f32_dpp v168, v168, v168 row_shr:1 row_mask:0xf bank_mask:0xf
	v_mul_f32_dpp v169, v169, v169 row_shr:1 row_mask:0xf bank_mask:0xf
	v_fmac_f32_dpp v204, v204, v166 row_shr:2 row_mask:0xf bank_mask:0xf bound_ctrl:1
	v_fmac_f32_dpp v205, v205, v167 row_shr:2 row_mask:0xf bank_mask:0xf bound_ctrl:1
	v_fmac_f32_dpp v206, v206, v168 row_shr:2 row_mask:0xf bank_mask:0xf bound_ctrl:1
	v_fmac_f32_dpp v207, v207, v169 row_shr:2 row_mask:0xf bank_mask:0xf bound_ctrl:1
	v_mul_f32_dpp v166, v166, v166 row_shr:2 row_mask:0xf bank_mask:0xf
	v_mul_f32_dpp v167, v167, v167 row_shr:2 row_mask:0xf bank_mask:0xf
	v_mul_f32_dpp v168, v168, v168 row_shr:2 row_mask:0xf bank_mask:0xf
	v_mul_f32_dpp v169, v169, v169 row_shr:2 row_mask:0xf bank_mask:0xf
	v_fmac_f32_dpp v204, v204, v166 row_shr:4 row_mask:0xf bank_mask:0xf bound_ctrl:1
	v_fmac_f32_dpp v205, v205, v167 row_shr:4 row_mask:0xf bank_mask:0xf bound_ctrl:1
	v_fmac_f32_dpp v206, v206, v168 row_shr:4 row_mask:0xf bank_mask:0xf bound_ctrl:1
	v_fmac_f32_dpp v207, v207, v169 row_shr:4 row_mask:0xf bank_mask:0xf bound_ctrl:1
	v_mul_f32_dpp v166, v166, v166 row_shr:4 row_mask:0xf bank_mask:0xf
	v_mul_f32_dpp v167, v167, v167 row_shr:4 row_mask:0xf bank_mask:0xf
	v_mul_f32_dpp v168, v168, v168 row_shr:4 row_mask:0xf bank_mask:0xf
	v_mul_f32_dpp v169, v169, v169 row_shr:4 row_mask:0xf bank_mask:0xf
	v_fmac_f32_dpp v204, v204, v166 row_shr:8 row_mask:0xf bank_mask:0xf bound_ctrl:1
	v_fmac_f32_dpp v205, v205, v167 row_shr:8 row_mask:0xf bank_mask:0xf bound_ctrl:1
	v_fmac_f32_dpp v206, v206, v168 row_shr:8 row_mask:0xf bank_mask:0xf bound_ctrl:1
	v_fmac_f32_dpp v207, v207, v169 row_shr:8 row_mask:0xf bank_mask:0xf bound_ctrl:1
	v_mul_f32_dpp v166, v166, v166 row_shr:8 row_mask:0xf bank_mask:0xf
	v_mul_f32_dpp v167, v167, v167 row_shr:8 row_mask:0xf bank_mask:0xf
	v_mul_f32_dpp v168, v168, v168 row_shr:8 row_mask:0xf bank_mask:0xf
	v_mul_f32_dpp v169, v169, v169 row_shr:8 row_mask:0xf bank_mask:0xf
	v_fma_f32 v208, v166, v0, v204
	v_fma_f32 v209, v167, v1, v205
	v_fma_f32 v210, v168, v2, v206
	v_fma_f32 v211, v169, v3, v207
	v_mov_b32_dpp v0, v208 row_newbcast:15 row_mask:0xf bank_mask:0xf
	v_mov_b32_dpp v1, v209 row_newbcast:15 row_mask:0xf bank_mask:0xf
	v_mov_b32_dpp v2, v210 row_newbcast:15 row_mask:0xf bank_mask:0xf
	v_mov_b32_dpp v3, v211 row_newbcast:15 row_mask:0xf bank_mask:0xf
	v_mul_f32_dpp v24, v166, v24 row_newbcast:15 row_mask:0xf bank_mask:0xf
	v_mul_f32_dpp v25, v167, v25 row_newbcast:15 row_mask:0xf bank_mask:0xf
	v_mul_f32_dpp v26, v168, v26 row_newbcast:15 row_mask:0xf bank_mask:0xf
	v_mul_f32_dpp v27, v169, v27 row_newbcast:15 row_mask:0xf bank_mask:0xf
	ds_read_b128 v[110:113], v229 offset:6656
	ds_read_b128 v[122:125], v229 offset:26624
	ds_read_b128 v[114:117], v229 offset:6720
	ds_read_b128 v[126:129], v229 offset:26688
	ds_read_b128 v[118:121], v229 offset:6784
	ds_read_b128 v[130:133], v229 offset:26752
	v_pk_fma_f32 v[166:167], v[142:143], s[66:67], v[150:151] op_sel_hi:[1,0,1]
	v_pk_fma_f32 v[168:169], v[144:145], s[66:67], v[152:153] op_sel_hi:[1,0,1]
	v_pk_fma_f32 v[204:205], v[146:147], s[66:67], v[154:155] op_sel_hi:[1,0,1]
	v_pk_fma_f32 v[206:207], v[148:149], s[66:67], v[156:157] op_sel_hi:[1,0,1]
	v_exp_f32_e32 v166, v166
	v_exp_f32_e32 v167, v167
	v_exp_f32_e32 v168, v168
	v_exp_f32_e32 v169, v169
	v_exp_f32_e32 v204, v204
	v_exp_f32_e32 v205, v205
	v_exp_f32_e32 v206, v206
	v_exp_f32_e32 v207, v207
	v_pk_add_f32 v[166:167], v[166:167], 1.0 op_sel_hi:[1,0]
	v_pk_add_f32 v[168:169], v[168:169], 1.0 op_sel_hi:[1,0]
	v_pk_add_f32 v[204:205], v[204:205], 1.0 op_sel_hi:[1,0]
	v_pk_add_f32 v[206:207], v[206:207], 1.0 op_sel_hi:[1,0]
	v_rcp_f32_e32 v166, v166
	v_rcp_f32_e32 v167, v167
	v_rcp_f32_e32 v168, v168
	v_rcp_f32_e32 v169, v169
	v_rcp_f32_e32 v204, v204
	v_rcp_f32_e32 v205, v205
	v_rcp_f32_e32 v206, v206
	v_rcp_f32_e32 v207, v207
	v_pk_mul_f32 v[208:209], v[158:159], v[166:167]
	v_pk_mul_f32 v[210:211], v[160:161], v[168:169]
	v_pk_mul_f32 v[204:205], v[162:163], v[204:205]
	v_pk_mul_f32 v[206:207], v[164:165], v[206:207]
	ds_read_b128 v[150:153], v230 offset:128
	ds_read_b128 v[154:157], v230 offset:512
	ds_read_b128 v[158:161], v230 offset:896
	ds_read_b128 v[162:165], v231 offset:128
	v_exp_f32_e32 v166, v208
	v_exp_f32_e32 v167, v209
	v_exp_f32_e32 v168, v210
	v_exp_f32_e32 v169, v211
	v_pk_fma_f32 v[216:217], v[208:209], s[66:67], v[248:249] op_sel:[0,1,0] op_sel_hi:[1,1,0]
	v_pk_fma_f32 v[218:219], v[210:211], s[66:67], v[248:249] op_sel:[0,1,0] op_sel_hi:[1,1,0]
	v_pk_fma_f32 v[216:217], v[208:209], v[216:217], v[248:249] op_sel:[0,0,1] op_sel_hi:[1,1,1]
	v_pk_fma_f32 v[218:219], v[210:211], v[218:219], v[248:249] op_sel:[0,0,1] op_sel_hi:[1,1,1]
	v_min3_f32 v212, v208, v209, v210
	v_pk_fma_f32 v[216:217], v[208:209], v[216:217], v[250:251] op_sel_hi:[1,1,0]
	v_pk_fma_f32 v[218:219], v[210:211], v[218:219], v[250:251] op_sel_hi:[1,1,0]
	v_min_f32_e32 v212, v212, v211
	v_pk_fma_f32 v[216:217], v[208:209], v[216:217], v[250:251] op_sel:[0,0,1] op_sel_hi:[1,1,1]
	v_pk_fma_f32 v[218:219], v[210:211], v[218:219], v[250:251] op_sel:[0,0,1] op_sel_hi:[1,1,1]
	v_cmp_nlt_f32_e32 vcc, 0xbe38aa3b, v212
	v_pk_mul_f32 v[216:217], v[216:217], v[208:209]
	v_pk_mul_f32 v[218:219], v[218:219], v[210:211]
	s_cbranch_vccnz .Lscan1_far1
.Lscan1_back1:
	v_sqrt_f32_e32 v216, v216
	v_sqrt_f32_e32 v217, v217
	v_sqrt_f32_e32 v218, v218
	v_sqrt_f32_e32 v219, v219
	v_pk_mul_f32 v[204:205], v[204:205], v[216:217]
	v_pk_mul_f32 v[206:207], v[206:207], v[218:219]
	s_waitcnt lgkmcnt(0)
	v_mfma_f32_16x16x32_bf16 v[134:137], v[110:113], v[98:101], 0
	v_mfma_f32_16x16x32_bf16 v[138:141], v[122:125], v[98:101], 0
	v_mfma_f32_16x16x32_bf16 v[134:137], v[114:117], v[102:105], v[134:137]
	v_mfma_f32_16x16x32_bf16 v[138:141], v[126:129], v[102:105], v[138:141]
	v_mfma_f32_16x16x32_bf16 v[134:137], v[118:121], v[106:109], v[134:137]
	v_mfma_f32_16x16x32_bf16 v[138:141], v[130:133], v[106:109], v[138:141]
	s_nop 1
	v_fmac_f32_dpp v204, v204, v166 row_shr:1 row_mask:0xf bank_mask:0xf bound_ctrl:1
	v_fmac_f32_dpp v205, v205, v167 row_shr:1 row_mask:0xf bank_mask:0xf bound_ctrl:1
	v_fmac_f32_dpp v206, v206, v168 row_shr:1 row_mask:0xf bank_mask:0xf bound_ctrl:1
	v_fmac_f32_dpp v207, v207, v169 row_shr:1 row_mask:0xf bank_mask:0xf bound_ctrl:1
	v_mul_f32_dpp v166, v166, v166 row_shr:1 row_mask:0xf bank_mask:0xf
	v_mul_f32_dpp v167, v167, v167 row_shr:1 row_mask:0xf bank_mask:0xf
	v_mul_f32_dpp v168, v168, v168 row_shr:1 row_mask:0xf bank_mask:0xf
	v_mul_f32_dpp v169, v169, v169 row_shr:1 row_mask:0xf bank_mask:0xf
	v_fmac_f32_dpp v204, v204, v166 row_shr:2 row_mask:0xf bank_mask:0xf bound_ctrl:1
	v_fmac_f32_dpp v205, v205, v167 row_shr:2 row_mask:0xf bank_mask:0xf bound_ctrl:1
	v_fmac_f32_dpp v206, v206, v168 row_shr:2 row_mask:0xf bank_mask:0xf bound_ctrl:1
	v_fmac_f32_dpp v207, v207, v169 row_shr:2 row_mask:0xf bank_mask:0xf bound_ctrl:1
	v_mul_f32_dpp v166, v166, v166 row_shr:2 row_mask:0xf bank_mask:0xf
	v_mul_f32_dpp v167, v167, v167 row_shr:2 row_mask:0xf bank_mask:0xf
	v_mul_f32_dpp v168, v168, v168 row_shr:2 row_mask:0xf bank_mask:0xf
	v_mul_f32_dpp v169, v169, v169 row_shr:2 row_mask:0xf bank_mask:0xf
	v_fmac_f32_dpp v204, v204, v166 row_shr:4 row_mask:0xf bank_mask:0xf bound_ctrl:1
	v_fmac_f32_dpp v205, v205, v167 row_shr:4 row_mask:0xf bank_mask:0xf bound_ctrl:1
	v_fmac_f32_dpp v206, v206, v168 row_shr:4 row_mask:0xf bank_mask:0xf bound_ctrl:1
	v_fmac_f32_dpp v207, v207, v169 row_shr:4 row_mask:0xf bank_mask:0xf bound_ctrl:1
	v_mul_f32_dpp v166, v166, v166 row_shr:4 row_mask:0xf bank_mask:0xf
	v_mul_f32_dpp v167, v167, v167 row_shr:4 row_mask:0xf bank_mask:0xf
	v_mul_f32_dpp v168, v168, v168 row_shr:4 row_mask:0xf bank_mask:0xf
	v_mul_f32_dpp v169, v169, v169 row_shr:4 row_mask:0xf bank_mask:0xf
	v_fmac_f32_dpp v204, v204, v166 row_shr:8 row_mask:0xf bank_mask:0xf bound_ctrl:1
	v_fmac_f32_dpp v205, v205, v167 row_shr:8 row_mask:0xf bank_mask:0xf bound_ctrl:1
	v_fmac_f32_dpp v206, v206, v168 row_shr:8 row_mask:0xf bank_mask:0xf bound_ctrl:1
	v_fmac_f32_dpp v207, v207, v169 row_shr:8 row_mask:0xf bank_mask:0xf bound_ctrl:1
	v_mul_f32_dpp v166, v166, v166 row_shr:8 row_mask:0xf bank_mask:0xf
	v_mul_f32_dpp v167, v167, v167 row_shr:8 row_mask:0xf bank_mask:0xf
	v_mul_f32_dpp v168, v168, v168 row_shr:8 row_mask:0xf bank_mask:0xf
	v_mul_f32_dpp v169, v169, v169 row_shr:8 row_mask:0xf bank_mask:0xf
	v_fma_f32 v208, v166, v4, v204
	v_fma_f32 v209, v167, v5, v205
	v_fma_f32 v210, v168, v6, v206
	v_fma_f32 v211, v169, v7, v207
	v_mov_b32_dpp v4, v208 row_newbcast:15 row_mask:0xf bank_mask:0xf
	v_mov_b32_dpp v5, v209 row_newbcast:15 row_mask:0xf bank_mask:0xf
	v_mov_b32_dpp v6, v210 row_newbcast:15 row_mask:0xf bank_mask:0xf
	v_mov_b32_dpp v7, v211 row_newbcast:15 row_mask:0xf bank_mask:0xf
	v_mul_f32_dpp v28, v166, v28 row_newbcast:15 row_mask:0xf bank_mask:0xf
	v_mul_f32_dpp v29, v167, v29 row_newbcast:15 row_mask:0xf bank_mask:0xf
	v_mul_f32_dpp v30, v168, v30 row_newbcast:15 row_mask:0xf bank_mask:0xf
	v_mul_f32_dpp v31, v169, v31 row_newbcast:15 row_mask:0xf bank_mask:0xf
	ds_read_b128 v[110:113], v229 offset:9984
	ds_read_b128 v[122:125], v229 offset:29952
	ds_read_b128 v[114:117], v229 offset:10048
	ds_read_b128 v[126:129], v229 offset:30016
	ds_read_b128 v[118:121], v229 offset:10112
	ds_read_b128 v[130:133], v229 offset:30080
	v_pk_fma_f32 v[166:167], v[134:135], s[66:67], v[150:151] op_sel_hi:[1,0,1]
	v_pk_fma_f32 v[168:169], v[136:137], s[66:67], v[152:153] op_sel_hi:[1,0,1]
	v_pk_fma_f32 v[204:205], v[138:139], s[66:67], v[154:155] op_sel_hi:[1,0,1]
	v_pk_fma_f32 v[206:207], v[140:141], s[66:67], v[156:157] op_sel_hi:[1,0,1]
	v_exp_f32_e32 v166, v166
	v_exp_f32_e32 v167, v167
	v_exp_f32_e32 v168, v168
	v_exp_f32_e32 v169, v169
	v_exp_f32_e32 v204, v204
	v_exp_f32_e32 v205, v205
	v_exp_f32_e32 v206, v206
	v_exp_f32_e32 v207, v207
	v_pk_add_f32 v[166:167], v[166:167], 1.0 op_sel_hi:[1,0]
	v_pk_add_f32 v[168:169], v[168:169], 1.0 op_sel_hi:[1,0]
	v_pk_add_f32 v[204:205], v[204:205], 1.0 op_sel_hi:[1,0]
	v_pk_add_f32 v[206:207], v[206:207], 1.0 op_sel_hi:[1,0]
	v_rcp_f32_e32 v166, v166
	v_rcp_f32_e32 v167, v167
	v_rcp_f32_e32 v168, v168
	v_rcp_f32_e32 v169, v169
	v_rcp_f32_e32 v204, v204
	v_rcp_f32_e32 v205, v205
	v_rcp_f32_e32 v206, v206
	v_rcp_f32_e32 v207, v207
	v_pk_mul_f32 v[208:209], v[158:159], v[166:167]
	v_pk_mul_f32 v[210:211], v[160:161], v[168:169]
	v_pk_mul_f32 v[204:205], v[162:163], v[204:205]
	v_pk_mul_f32 v[206:207], v[164:165], v[206:207]
	ds_read_b128 v[150:153], v230 offset:192
	ds_read_b128 v[154:157], v230 offset:576
	ds_read_b128 v[158:161], v230 offset:960
	ds_read_b128 v[162:165], v231 offset:192
	v_exp_f32_e32 v166, v208
	v_exp_f32_e32 v167, v209
	v_exp_f32_e32 v168, v210
	v_exp_f32_e32 v169, v211
	v_pk_fma_f32 v[216:217], v[208:209], s[66:67], v[248:249] op_sel:[0,1,0] op_sel_hi:[1,1,0]
	v_pk_fma_f32 v[218:219], v[210:211], s[66:67], v[248:249] op_sel:[0,1,0] op_sel_hi:[1,1,0]
	v_pk_fma_f32 v[216:217], v[208:209], v[216:217], v[248:249] op_sel:[0,0,1] op_sel_hi:[1,1,1]
	v_pk_fma_f32 v[218:219], v[210:211], v[218:219], v[248:249] op_sel:[0,0,1] op_sel_hi:[1,1,1]
	v_min3_f32 v212, v208, v209, v210
	v_pk_fma_f32 v[216:217], v[208:209], v[216:217], v[250:251] op_sel_hi:[1,1,0]
	v_pk_fma_f32 v[218:219], v[210:211], v[218:219], v[250:251] op_sel_hi:[1,1,0]
	v_min_f32_e32 v212, v212, v211
	v_pk_fma_f32 v[216:217], v[208:209], v[216:217], v[250:251] op_sel:[0,0,1] op_sel_hi:[1,1,1]
	v_pk_fma_f32 v[218:219], v[210:211], v[218:219], v[250:251] op_sel:[0,0,1] op_sel_hi:[1,1,1]
	v_cmp_nlt_f32_e32 vcc, 0xbe38aa3b, v212
	v_pk_mul_f32 v[216:217], v[216:217], v[208:209]
	v_pk_mul_f32 v[218:219], v[218:219], v[210:211]
	s_cbranch_vccnz .Lscan1_far2
.Lscan1_back2:
	v_sqrt_f32_e32 v216, v216
	v_sqrt_f32_e32 v217, v217
	v_sqrt_f32_e32 v218, v218
	v_sqrt_f32_e32 v219, v219
	v_pk_mul_f32 v[204:205], v[204:205], v[216:217]
	v_pk_mul_f32 v[206:207], v[206:207], v[218:219]
	s_waitcnt lgkmcnt(0)
	v_mfma_f32_16x16x32_bf16 v[142:145], v[110:113], v[98:101], 0
	v_mfma_f32_16x16x32_bf16 v[146:149], v[122:125], v[98:101], 0
	v_mfma_f32_16x16x32_bf16 v[142:145], v[114:117], v[102:105], v[142:145]
	v_mfma_f32_16x16x32_bf16 v[146:149], v[126:129], v[102:105], v[146:149]
	v_mfma_f32_16x16x32_bf16 v[142:145], v[118:121], v[106:109], v[142:145]
	v_mfma_f32_16x16x32_bf16 v[146:149], v[130:133], v[106:109], v[146:149]
	s_nop 1
	v_fmac_f32_dpp v204, v204, v166 row_shr:1 row_mask:0xf bank_mask:0xf bound_ctrl:1
	v_fmac_f32_dpp v205, v205, v167 row_shr:1 row_mask:0xf bank_mask:0xf bound_ctrl:1
	v_fmac_f32_dpp v206, v206, v168 row_shr:1 row_mask:0xf bank_mask:0xf bound_ctrl:1
	v_fmac_f32_dpp v207, v207, v169 row_shr:1 row_mask:0xf bank_mask:0xf bound_ctrl:1
	v_mul_f32_dpp v166, v166, v166 row_shr:1 row_mask:0xf bank_mask:0xf
	v_mul_f32_dpp v167, v167, v167 row_shr:1 row_mask:0xf bank_mask:0xf
	v_mul_f32_dpp v168, v168, v168 row_shr:1 row_mask:0xf bank_mask:0xf
	v_mul_f32_dpp v169, v169, v169 row_shr:1 row_mask:0xf bank_mask:0xf
	v_fmac_f32_dpp v204, v204, v166 row_shr:2 row_mask:0xf bank_mask:0xf bound_ctrl:1
	v_fmac_f32_dpp v205, v205, v167 row_shr:2 row_mask:0xf bank_mask:0xf bound_ctrl:1
	v_fmac_f32_dpp v206, v206, v168 row_shr:2 row_mask:0xf bank_mask:0xf bound_ctrl:1
	v_fmac_f32_dpp v207, v207, v169 row_shr:2 row_mask:0xf bank_mask:0xf bound_ctrl:1
	v_mul_f32_dpp v166, v166, v166 row_shr:2 row_mask:0xf bank_mask:0xf
	v_mul_f32_dpp v167, v167, v167 row_shr:2 row_mask:0xf bank_mask:0xf
	v_mul_f32_dpp v168, v168, v168 row_shr:2 row_mask:0xf bank_mask:0xf
	v_mul_f32_dpp v169, v169, v169 row_shr:2 row_mask:0xf bank_mask:0xf
	v_fmac_f32_dpp v204, v204, v166 row_shr:4 row_mask:0xf bank_mask:0xf bound_ctrl:1
	v_fmac_f32_dpp v205, v205, v167 row_shr:4 row_mask:0xf bank_mask:0xf bound_ctrl:1
	v_fmac_f32_dpp v206, v206, v168 row_shr:4 row_mask:0xf bank_mask:0xf bound_ctrl:1
	v_fmac_f32_dpp v207, v207, v169 row_shr:4 row_mask:0xf bank_mask:0xf bound_ctrl:1
	v_mul_f32_dpp v166, v166, v166 row_shr:4 row_mask:0xf bank_mask:0xf
	v_mul_f32_dpp v167, v167, v167 row_shr:4 row_mask:0xf bank_mask:0xf
	v_mul_f32_dpp v168, v168, v168 row_shr:4 row_mask:0xf bank_mask:0xf
	v_mul_f32_dpp v169, v169, v169 row_shr:4 row_mask:0xf bank_mask:0xf
	v_fmac_f32_dpp v204, v204, v166 row_shr:8 row_mask:0xf bank_mask:0xf bound_ctrl:1
	v_fmac_f32_dpp v205, v205, v167 row_shr:8 row_mask:0xf bank_mask:0xf bound_ctrl:1
	v_fmac_f32_dpp v206, v206, v168 row_shr:8 row_mask:0xf bank_mask:0xf bound_ctrl:1
	v_fmac_f32_dpp v207, v207, v169 row_shr:8 row_mask:0xf bank_mask:0xf bound_ctrl:1
	v_mul_f32_dpp v166, v166, v166 row_shr:8 row_mask:0xf bank_mask:0xf
	v_mul_f32_dpp v167, v167, v167 row_shr:8 row_mask:0xf bank_mask:0xf
	v_mul_f32_dpp v168, v168, v168 row_shr:8 row_mask:0xf bank_mask:0xf
	v_mul_f32_dpp v169, v169, v169 row_shr:8 row_mask:0xf bank_mask:0xf
	v_fma_f32 v208, v166, v8, v204
	v_fma_f32 v209, v167, v9, v205
	v_fma_f32 v210, v168, v10, v206
	v_fma_f32 v211, v169, v11, v207
	v_mov_b32_dpp v8, v208 row_newbcast:15 row_mask:0xf bank_mask:0xf
	v_mov_b32_dpp v9, v209 row_newbcast:15 row_mask:0xf bank_mask:0xf
	v_mov_b32_dpp v10, v210 row_newbcast:15 row_mask:0xf bank_mask:0xf
	v_mov_b32_dpp v11, v211 row_newbcast:15 row_mask:0xf bank_mask:0xf
	v_mul_f32_dpp v32, v166, v32 row_newbcast:15 row_mask:0xf bank_mask:0xf
	v_mul_f32_dpp v33, v167, v33 row_newbcast:15 row_mask:0xf bank_mask:0xf
	v_mul_f32_dpp v34, v168, v34 row_newbcast:15 row_mask:0xf bank_mask:0xf
	v_mul_f32_dpp v35, v169, v35 row_newbcast:15 row_mask:0xf bank_mask:0xf
	ds_read_b128 v[110:113], v229 offset:13312
	ds_read_b128 v[122:125], v229 offset:33280
	ds_read_b128 v[114:117], v229 offset:13376
	ds_read_b128 v[126:129], v229 offset:33344
	ds_read_b128 v[118:121], v229 offset:13440
	ds_read_b128 v[130:133], v229 offset:33408
	v_pk_fma_f32 v[166:167], v[142:143], s[66:67], v[150:151] op_sel_hi:[1,0,1]
	v_pk_fma_f32 v[168:169], v[144:145], s[66:67], v[152:153] op_sel_hi:[1,0,1]
	v_pk_fma_f32 v[204:205], v[146:147], s[66:67], v[154:155] op_sel_hi:[1,0,1]
	v_pk_fma_f32 v[206:207], v[148:149], s[66:67], v[156:157] op_sel_hi:[1,0,1]
	v_exp_f32_e32 v166, v166
	v_exp_f32_e32 v167, v167
	v_exp_f32_e32 v168, v168
	v_exp_f32_e32 v169, v169
	v_exp_f32_e32 v204, v204
	v_exp_f32_e32 v205, v205
	v_exp_f32_e32 v206, v206
	v_exp_f32_e32 v207, v207
	v_pk_add_f32 v[166:167], v[166:167], 1.0 op_sel_hi:[1,0]
	v_pk_add_f32 v[168:169], v[168:169], 1.0 op_sel_hi:[1,0]
	v_pk_add_f32 v[204:205], v[204:205], 1.0 op_sel_hi:[1,0]
	v_pk_add_f32 v[206:207], v[206:207], 1.0 op_sel_hi:[1,0]
	v_rcp_f32_e32 v166, v166
	v_rcp_f32_e32 v167, v167
	v_rcp_f32_e32 v168, v168
	v_rcp_f32_e32 v169, v169
	v_rcp_f32_e32 v204, v204
	v_rcp_f32_e32 v205, v205
	v_rcp_f32_e32 v206, v206
	v_rcp_f32_e32 v207, v207
	v_pk_mul_f32 v[208:209], v[158:159], v[166:167]
	v_pk_mul_f32 v[210:211], v[160:161], v[168:169]
	v_pk_mul_f32 v[204:205], v[162:163], v[204:205]
	v_pk_mul_f32 v[206:207], v[164:165], v[206:207]
	ds_read_b128 v[150:153], v230 offset:256
	ds_read_b128 v[154:157], v230 offset:640
	ds_read_b128 v[158:161], v230 offset:1024
	ds_read_b128 v[162:165], v231 offset:256
	v_exp_f32_e32 v166, v208
	v_exp_f32_e32 v167, v209
	v_exp_f32_e32 v168, v210
	v_exp_f32_e32 v169, v211
	v_pk_fma_f32 v[216:217], v[208:209], s[66:67], v[248:249] op_sel:[0,1,0] op_sel_hi:[1,1,0]
	v_pk_fma_f32 v[218:219], v[210:211], s[66:67], v[248:249] op_sel:[0,1,0] op_sel_hi:[1,1,0]
	v_pk_fma_f32 v[216:217], v[208:209], v[216:217], v[248:249] op_sel:[0,0,1] op_sel_hi:[1,1,1]
	v_pk_fma_f32 v[218:219], v[210:211], v[218:219], v[248:249] op_sel:[0,0,1] op_sel_hi:[1,1,1]
	v_min3_f32 v212, v208, v209, v210
	v_pk_fma_f32 v[216:217], v[208:209], v[216:217], v[250:251] op_sel_hi:[1,1,0]
	v_pk_fma_f32 v[218:219], v[210:211], v[218:219], v[250:251] op_sel_hi:[1,1,0]
	v_min_f32_e32 v212, v212, v211
	v_pk_fma_f32 v[216:217], v[208:209], v[216:217], v[250:251] op_sel:[0,0,1] op_sel_hi:[1,1,1]
	v_pk_fma_f32 v[218:219], v[210:211], v[218:219], v[250:251] op_sel:[0,0,1] op_sel_hi:[1,1,1]
	v_cmp_nlt_f32_e32 vcc, 0xbe38aa3b, v212
	v_pk_mul_f32 v[216:217], v[216:217], v[208:209]
	v_pk_mul_f32 v[218:219], v[218:219], v[210:211]
	s_cbranch_vccnz .Lscan1_far3
.Lscan1_back3:
	v_sqrt_f32_e32 v216, v216
	v_sqrt_f32_e32 v217, v217
	v_sqrt_f32_e32 v218, v218
	v_sqrt_f32_e32 v219, v219
	v_pk_mul_f32 v[204:205], v[204:205], v[216:217]
	v_pk_mul_f32 v[206:207], v[206:207], v[218:219]
	s_waitcnt lgkmcnt(0)
	v_mfma_f32_16x16x32_bf16 v[134:137], v[110:113], v[98:101], 0
	v_mfma_f32_16x16x32_bf16 v[138:141], v[122:125], v[98:101], 0
	v_mfma_f32_16x16x32_bf16 v[134:137], v[114:117], v[102:105], v[134:137]
	v_mfma_f32_16x16x32_bf16 v[138:141], v[126:129], v[102:105], v[138:141]
	v_mfma_f32_16x16x32_bf16 v[134:137], v[118:121], v[106:109], v[134:137]
	v_mfma_f32_16x16x32_bf16 v[138:141], v[130:133], v[106:109], v[138:141]
	s_nop 1
	v_fmac_f32_dpp v204, v204, v166 row_shr:1 row_mask:0xf bank_mask:0xf bound_ctrl:1
	v_fmac_f32_dpp v205, v205, v167 row_shr:1 row_mask:0xf bank_mask:0xf bound_ctrl:1
	v_fmac_f32_dpp v206, v206, v168 row_shr:1 row_mask:0xf bank_mask:0xf bound_ctrl:1
	v_fmac_f32_dpp v207, v207, v169 row_shr:1 row_mask:0xf bank_mask:0xf bound_ctrl:1
	v_mul_f32_dpp v166, v166, v166 row_shr:1 row_mask:0xf bank_mask:0xf
	v_mul_f32_dpp v167, v167, v167 row_shr:1 row_mask:0xf bank_mask:0xf
	v_mul_f32_dpp v168, v168, v168 row_shr:1 row_mask:0xf bank_mask:0xf
	v_mul_f32_dpp v169, v169, v169 row_shr:1 row_mask:0xf bank_mask:0xf
	v_fmac_f32_dpp v204, v204, v166 row_shr:2 row_mask:0xf bank_mask:0xf bound_ctrl:1
	v_fmac_f32_dpp v205, v205, v167 row_shr:2 row_mask:0xf bank_mask:0xf bound_ctrl:1
	v_fmac_f32_dpp v206, v206, v168 row_shr:2 row_mask:0xf bank_mask:0xf bound_ctrl:1
	v_fmac_f32_dpp v207, v207, v169 row_shr:2 row_mask:0xf bank_mask:0xf bound_ctrl:1
	v_mul_f32_dpp v166, v166, v166 row_shr:2 row_mask:0xf bank_mask:0xf
	v_mul_f32_dpp v167, v167, v167 row_shr:2 row_mask:0xf bank_mask:0xf
	v_mul_f32_dpp v168, v168, v168 row_shr:2 row_mask:0xf bank_mask:0xf
	v_mul_f32_dpp v169, v169, v169 row_shr:2 row_mask:0xf bank_mask:0xf
	v_fmac_f32_dpp v204, v204, v166 row_shr:4 row_mask:0xf bank_mask:0xf bound_ctrl:1
	v_fmac_f32_dpp v205, v205, v167 row_shr:4 row_mask:0xf bank_mask:0xf bound_ctrl:1
	v_fmac_f32_dpp v206, v206, v168 row_shr:4 row_mask:0xf bank_mask:0xf bound_ctrl:1
	v_fmac_f32_dpp v207, v207, v169 row_shr:4 row_mask:0xf bank_mask:0xf bound_ctrl:1
	v_mul_f32_dpp v166, v166, v166 row_shr:4 row_mask:0xf bank_mask:0xf
	v_mul_f32_dpp v167, v167, v167 row_shr:4 row_mask:0xf bank_mask:0xf
	v_mul_f32_dpp v168, v168, v168 row_shr:4 row_mask:0xf bank_mask:0xf
	v_mul_f32_dpp v169, v169, v169 row_shr:4 row_mask:0xf bank_mask:0xf
	v_fmac_f32_dpp v204, v204, v166 row_shr:8 row_mask:0xf bank_mask:0xf bound_ctrl:1
	v_fmac_f32_dpp v205, v205, v167 row_shr:8 row_mask:0xf bank_mask:0xf bound_ctrl:1
	v_fmac_f32_dpp v206, v206, v168 row_shr:8 row_mask:0xf bank_mask:0xf bound_ctrl:1
	v_fmac_f32_dpp v207, v207, v169 row_shr:8 row_mask:0xf bank_mask:0xf bound_ctrl:1
	v_mul_f32_dpp v166, v166, v166 row_shr:8 row_mask:0xf bank_mask:0xf
	v_mul_f32_dpp v167, v167, v167 row_shr:8 row_mask:0xf bank_mask:0xf
	v_mul_f32_dpp v168, v168, v168 row_shr:8 row_mask:0xf bank_mask:0xf
	v_mul_f32_dpp v169, v169, v169 row_shr:8 row_mask:0xf bank_mask:0xf
	v_fma_f32 v208, v166, v12, v204
	v_fma_f32 v209, v167, v13, v205
	v_fma_f32 v210, v168, v14, v206
	v_fma_f32 v211, v169, v15, v207
	v_mov_b32_dpp v12, v208 row_newbcast:15 row_mask:0xf bank_mask:0xf
	v_mov_b32_dpp v13, v209 row_newbcast:15 row_mask:0xf bank_mask:0xf
	v_mov_b32_dpp v14, v210 row_newbcast:15 row_mask:0xf bank_mask:0xf
	v_mov_b32_dpp v15, v211 row_newbcast:15 row_mask:0xf bank_mask:0xf
	v_mul_f32_dpp v36, v166, v36 row_newbcast:15 row_mask:0xf bank_mask:0xf
	v_mul_f32_dpp v37, v167, v37 row_newbcast:15 row_mask:0xf bank_mask:0xf
	v_mul_f32_dpp v38, v168, v38 row_newbcast:15 row_mask:0xf bank_mask:0xf
	v_mul_f32_dpp v39, v169, v39 row_newbcast:15 row_mask:0xf bank_mask:0xf
	ds_read_b128 v[110:113], v229 offset:16640
	ds_read_b128 v[122:125], v229 offset:36608
	ds_read_b128 v[114:117], v229 offset:16704
	ds_read_b128 v[126:129], v229 offset:36672
	ds_read_b128 v[118:121], v229 offset:16768
	ds_read_b128 v[130:133], v229 offset:36736
	v_pk_fma_f32 v[166:167], v[134:135], s[66:67], v[150:151] op_sel_hi:[1,0,1]
	v_pk_fma_f32 v[168:169], v[136:137], s[66:67], v[152:153] op_sel_hi:[1,0,1]
	v_pk_fma_f32 v[204:205], v[138:139], s[66:67], v[154:155] op_sel_hi:[1,0,1]
	v_pk_fma_f32 v[206:207], v[140:141], s[66:67], v[156:157] op_sel_hi:[1,0,1]
	v_exp_f32_e32 v166, v166
	v_exp_f32_e32 v167, v167
	v_exp_f32_e32 v168, v168
	v_exp_f32_e32 v169, v169
	v_exp_f32_e32 v204, v204
	v_exp_f32_e32 v205, v205
	v_exp_f32_e32 v206, v206
	v_exp_f32_e32 v207, v207
	v_pk_add_f32 v[166:167], v[166:167], 1.0 op_sel_hi:[1,0]
	v_pk_add_f32 v[168:169], v[168:169], 1.0 op_sel_hi:[1,0]
	v_pk_add_f32 v[204:205], v[204:205], 1.0 op_sel_hi:[1,0]
	v_pk_add_f32 v[206:207], v[206:207], 1.0 op_sel_hi:[1,0]
	v_rcp_f32_e32 v166, v166
	v_rcp_f32_e32 v167, v167
	v_rcp_f32_e32 v168, v168
	v_rcp_f32_e32 v169, v169
	v_rcp_f32_e32 v204, v204
	v_rcp_f32_e32 v205, v205
	v_rcp_f32_e32 v206, v206
	v_rcp_f32_e32 v207, v207
	v_pk_mul_f32 v[208:209], v[158:159], v[166:167]
	v_pk_mul_f32 v[210:211], v[160:161], v[168:169]
	v_pk_mul_f32 v[204:205], v[162:163], v[204:205]
	v_pk_mul_f32 v[206:207], v[164:165], v[206:207]
	ds_read_b128 v[150:153], v230 offset:320
	ds_read_b128 v[154:157], v230 offset:704
	ds_read_b128 v[158:161], v230 offset:1088
	ds_read_b128 v[162:165], v231 offset:320
	v_exp_f32_e32 v166, v208
	v_exp_f32_e32 v167, v209
	v_exp_f32_e32 v168, v210
	v_exp_f32_e32 v169, v211
	v_pk_fma_f32 v[216:217], v[208:209], s[66:67], v[248:249] op_sel:[0,1,0] op_sel_hi:[1,1,0]
	v_pk_fma_f32 v[218:219], v[210:211], s[66:67], v[248:249] op_sel:[0,1,0] op_sel_hi:[1,1,0]
	v_pk_fma_f32 v[216:217], v[208:209], v[216:217], v[248:249] op_sel:[0,0,1] op_sel_hi:[1,1,1]
	v_pk_fma_f32 v[218:219], v[210:211], v[218:219], v[248:249] op_sel:[0,0,1] op_sel_hi:[1,1,1]
	v_min3_f32 v212, v208, v209, v210
	v_pk_fma_f32 v[216:217], v[208:209], v[216:217], v[250:251] op_sel_hi:[1,1,0]
	v_pk_fma_f32 v[218:219], v[210:211], v[218:219], v[250:251] op_sel_hi:[1,1,0]
	v_min_f32_e32 v212, v212, v211
	v_pk_fma_f32 v[216:217], v[208:209], v[216:217], v[250:251] op_sel:[0,0,1] op_sel_hi:[1,1,1]
	v_pk_fma_f32 v[218:219], v[210:211], v[218:219], v[250:251] op_sel:[0,0,1] op_sel_hi:[1,1,1]
	v_cmp_nlt_f32_e32 vcc, 0xbe38aa3b, v212
	v_pk_mul_f32 v[216:217], v[216:217], v[208:209]
	v_pk_mul_f32 v[218:219], v[218:219], v[210:211]
	s_cbranch_vccnz .Lscan1_far4
.Lscan1_back4:
	v_sqrt_f32_e32 v216, v216
	v_sqrt_f32_e32 v217, v217
	v_sqrt_f32_e32 v218, v218
	v_sqrt_f32_e32 v219, v219
	v_pk_mul_f32 v[204:205], v[204:205], v[216:217]
	v_pk_mul_f32 v[206:207], v[206:207], v[218:219]
	s_waitcnt lgkmcnt(0)
	v_mfma_f32_16x16x32_bf16 v[142:145], v[110:113], v[98:101], 0
	v_mfma_f32_16x16x32_bf16 v[146:149], v[122:125], v[98:101], 0
	v_mfma_f32_16x16x32_bf16 v[142:145], v[114:117], v[102:105], v[142:145]
	v_mfma_f32_16x16x32_bf16 v[146:149], v[126:129], v[102:105], v[146:149]
	v_mfma_f32_16x16x32_bf16 v[142:145], v[118:121], v[106:109], v[142:145]
	v_mfma_f32_16x16x32_bf16 v[146:149], v[130:133], v[106:109], v[146:149]
	s_nop 1
	v_fmac_f32_dpp v204, v204, v166 row_shr:1 row_mask:0xf bank_mask:0xf bound_ctrl:1
	v_fmac_f32_dpp v205, v205, v167 row_shr:1 row_mask:0xf bank_mask:0xf bound_ctrl:1
	v_fmac_f32_dpp v206, v206, v168 row_shr:1 row_mask:0xf bank_mask:0xf bound_ctrl:1
	v_fmac_f32_dpp v207, v207, v169 row_shr:1 row_mask:0xf bank_mask:0xf bound_ctrl:1
	v_mul_f32_dpp v166, v166, v166 row_shr:1 row_mask:0xf bank_mask:0xf
	v_mul_f32_dpp v167, v167, v167 row_shr:1 row_mask:0xf bank_mask:0xf
	v_mul_f32_dpp v168, v168, v168 row_shr:1 row_mask:0xf bank_mask:0xf
	v_mul_f32_dpp v169, v169, v169 row_shr:1 row_mask:0xf bank_mask:0xf
	v_fmac_f32_dpp v204, v204, v166 row_shr:2 row_mask:0xf bank_mask:0xf bound_ctrl:1
	v_fmac_f32_dpp v205, v205, v167 row_shr:2 row_mask:0xf bank_mask:0xf bound_ctrl:1
	v_fmac_f32_dpp v206, v206, v168 row_shr:2 row_mask:0xf bank_mask:0xf bound_ctrl:1
	v_fmac_f32_dpp v207, v207, v169 row_shr:2 row_mask:0xf bank_mask:0xf bound_ctrl:1
	v_mul_f32_dpp v166, v166, v166 row_shr:2 row_mask:0xf bank_mask:0xf
	v_mul_f32_dpp v167, v167, v167 row_shr:2 row_mask:0xf bank_mask:0xf
	v_mul_f32_dpp v168, v168, v168 row_shr:2 row_mask:0xf bank_mask:0xf
	v_mul_f32_dpp v169, v169, v169 row_shr:2 row_mask:0xf bank_mask:0xf
	v_fmac_f32_dpp v204, v204, v166 row_shr:4 row_mask:0xf bank_mask:0xf bound_ctrl:1
	v_fmac_f32_dpp v205, v205, v167 row_shr:4 row_mask:0xf bank_mask:0xf bound_ctrl:1
	v_fmac_f32_dpp v206, v206, v168 row_shr:4 row_mask:0xf bank_mask:0xf bound_ctrl:1
	v_fmac_f32_dpp v207, v207, v169 row_shr:4 row_mask:0xf bank_mask:0xf bound_ctrl:1
	v_mul_f32_dpp v166, v166, v166 row_shr:4 row_mask:0xf bank_mask:0xf
	v_mul_f32_dpp v167, v167, v167 row_shr:4 row_mask:0xf bank_mask:0xf
	v_mul_f32_dpp v168, v168, v168 row_shr:4 row_mask:0xf bank_mask:0xf
	v_mul_f32_dpp v169, v169, v169 row_shr:4 row_mask:0xf bank_mask:0xf
	v_fmac_f32_dpp v204, v204, v166 row_shr:8 row_mask:0xf bank_mask:0xf bound_ctrl:1
	v_fmac_f32_dpp v205, v205, v167 row_shr:8 row_mask:0xf bank_mask:0xf bound_ctrl:1
	v_fmac_f32_dpp v206, v206, v168 row_shr:8 row_mask:0xf bank_mask:0xf bound_ctrl:1
	v_fmac_f32_dpp v207, v207, v169 row_shr:8 row_mask:0xf bank_mask:0xf bound_ctrl:1
	v_mul_f32_dpp v166, v166, v166 row_shr:8 row_mask:0xf bank_mask:0xf
	v_mul_f32_dpp v167, v167, v167 row_shr:8 row_mask:0xf bank_mask:0xf
	v_mul_f32_dpp v168, v168, v168 row_shr:8 row_mask:0xf bank_mask:0xf
	v_mul_f32_dpp v169, v169, v169 row_shr:8 row_mask:0xf bank_mask:0xf
	v_fma_f32 v208, v166, v16, v204
	v_fma_f32 v209, v167, v17, v205
	v_fma_f32 v210, v168, v18, v206
	v_fma_f32 v211, v169, v19, v207
	v_mov_b32_dpp v16, v208 row_newbcast:15 row_mask:0xf bank_mask:0xf
	v_mov_b32_dpp v17, v209 row_newbcast:15 row_mask:0xf bank_mask:0xf
	v_mov_b32_dpp v18, v210 row_newbcast:15 row_mask:0xf bank_mask:0xf
	v_mov_b32_dpp v19, v211 row_newbcast:15 row_mask:0xf bank_mask:0xf
	v_mul_f32_dpp v40, v166, v40 row_newbcast:15 row_mask:0xf bank_mask:0xf
	v_mul_f32_dpp v41, v167, v41 row_newbcast:15 row_mask:0xf bank_mask:0xf
	v_mul_f32_dpp v42, v168, v42 row_newbcast:15 row_mask:0xf bank_mask:0xf
	v_mul_f32_dpp v43, v169, v43 row_newbcast:15 row_mask:0xf bank_mask:0xf
	v_pk_fma_f32 v[166:167], v[142:143], s[66:67], v[150:151] op_sel_hi:[1,0,1]
	v_pk_fma_f32 v[168:169], v[144:145], s[66:67], v[152:153] op_sel_hi:[1,0,1]
	v_pk_fma_f32 v[204:205], v[146:147], s[66:67], v[154:155] op_sel_hi:[1,0,1]
	v_pk_fma_f32 v[206:207], v[148:149], s[66:67], v[156:157] op_sel_hi:[1,0,1]
	v_exp_f32_e32 v166, v166
	v_exp_f32_e32 v167, v167
	v_exp_f32_e32 v168, v168
	v_exp_f32_e32 v169, v169
	v_exp_f32_e32 v204, v204
	v_exp_f32_e32 v205, v205
	v_exp_f32_e32 v206, v206
	v_exp_f32_e32 v207, v207
	v_pk_add_f32 v[166:167], v[166:167], 1.0 op_sel_hi:[1,0]
	v_pk_add_f32 v[168:169], v[168:169], 1.0 op_sel_hi:[1,0]
	v_pk_add_f32 v[204:205], v[204:205], 1.0 op_sel_hi:[1,0]
	v_pk_add_f32 v[206:207], v[206:207], 1.0 op_sel_hi:[1,0]
	v_rcp_f32_e32 v166, v166
	v_rcp_f32_e32 v167, v167
	v_rcp_f32_e32 v168, v168
	v_rcp_f32_e32 v169, v169
	v_rcp_f32_e32 v204, v204
	v_rcp_f32_e32 v205, v205
	v_rcp_f32_e32 v206, v206
	v_rcp_f32_e32 v207, v207
	v_pk_mul_f32 v[208:209], v[158:159], v[166:167]
	v_pk_mul_f32 v[210:211], v[160:161], v[168:169]
	v_pk_mul_f32 v[204:205], v[162:163], v[204:205]
	v_pk_mul_f32 v[206:207], v[164:165], v[206:207]
	v_exp_f32_e32 v166, v208
	v_exp_f32_e32 v167, v209
	v_exp_f32_e32 v168, v210
	v_exp_f32_e32 v169, v211
	v_pk_fma_f32 v[216:217], v[208:209], s[66:67], v[248:249] op_sel:[0,1,0] op_sel_hi:[1,1,0]
	v_pk_fma_f32 v[218:219], v[210:211], s[66:67], v[248:249] op_sel:[0,1,0] op_sel_hi:[1,1,0]
	v_pk_fma_f32 v[216:217], v[208:209], v[216:217], v[248:249] op_sel:[0,0,1] op_sel_hi:[1,1,1]
	v_pk_fma_f32 v[218:219], v[210:211], v[218:219], v[248:249] op_sel:[0,0,1] op_sel_hi:[1,1,1]
	v_min3_f32 v212, v208, v209, v210
	v_pk_fma_f32 v[216:217], v[208:209], v[216:217], v[250:251] op_sel_hi:[1,1,0]
	v_pk_fma_f32 v[218:219], v[210:211], v[218:219], v[250:251] op_sel_hi:[1,1,0]
	v_min_f32_e32 v212, v212, v211
	v_pk_fma_f32 v[216:217], v[208:209], v[216:217], v[250:251] op_sel:[0,0,1] op_sel_hi:[1,1,1]
	v_pk_fma_f32 v[218:219], v[210:211], v[218:219], v[250:251] op_sel:[0,0,1] op_sel_hi:[1,1,1]
	v_cmp_nlt_f32_e32 vcc, 0xbe38aa3b, v212
	v_pk_mul_f32 v[216:217], v[216:217], v[208:209]
	v_pk_mul_f32 v[218:219], v[218:219], v[210:211]
	s_cbranch_vccnz .Lscan1_far5
.Lscan1_back5:
	v_sqrt_f32_e32 v216, v216
	v_sqrt_f32_e32 v217, v217
	v_sqrt_f32_e32 v218, v218
	v_sqrt_f32_e32 v219, v219
	v_pk_mul_f32 v[204:205], v[204:205], v[216:217]
	v_pk_mul_f32 v[206:207], v[206:207], v[218:219]
	s_waitcnt lgkmcnt(0)
	s_nop 1
	v_fmac_f32_dpp v204, v204, v166 row_shr:1 row_mask:0xf bank_mask:0xf bound_ctrl:1
	v_fmac_f32_dpp v205, v205, v167 row_shr:1 row_mask:0xf bank_mask:0xf bound_ctrl:1
	v_fmac_f32_dpp v206, v206, v168 row_shr:1 row_mask:0xf bank_mask:0xf bound_ctrl:1
	v_fmac_f32_dpp v207, v207, v169 row_shr:1 row_mask:0xf bank_mask:0xf bound_ctrl:1
	v_mul_f32_dpp v166, v166, v166 row_shr:1 row_mask:0xf bank_mask:0xf
	v_mul_f32_dpp v167, v167, v167 row_shr:1 row_mask:0xf bank_mask:0xf
	v_mul_f32_dpp v168, v168, v168 row_shr:1 row_mask:0xf bank_mask:0xf
	v_mul_f32_dpp v169, v169, v169 row_shr:1 row_mask:0xf bank_mask:0xf
	v_fmac_f32_dpp v204, v204, v166 row_shr:2 row_mask:0xf bank_mask:0xf bound_ctrl:1
	v_fmac_f32_dpp v205, v205, v167 row_shr:2 row_mask:0xf bank_mask:0xf bound_ctrl:1
	v_fmac_f32_dpp v206, v206, v168 row_shr:2 row_mask:0xf bank_mask:0xf bound_ctrl:1
	v_fmac_f32_dpp v207, v207, v169 row_shr:2 row_mask:0xf bank_mask:0xf bound_ctrl:1
	v_mul_f32_dpp v166, v166, v166 row_shr:2 row_mask:0xf bank_mask:0xf
	v_mul_f32_dpp v167, v167, v167 row_shr:2 row_mask:0xf bank_mask:0xf
	v_mul_f32_dpp v168, v168, v168 row_shr:2 row_mask:0xf bank_mask:0xf
	v_mul_f32_dpp v169, v169, v169 row_shr:2 row_mask:0xf bank_mask:0xf
	v_fmac_f32_dpp v204, v204, v166 row_shr:4 row_mask:0xf bank_mask:0xf bound_ctrl:1
	v_fmac_f32_dpp v205, v205, v167 row_shr:4 row_mask:0xf bank_mask:0xf bound_ctrl:1
	v_fmac_f32_dpp v206, v206, v168 row_shr:4 row_mask:0xf bank_mask:0xf bound_ctrl:1
	v_fmac_f32_dpp v207, v207, v169 row_shr:4 row_mask:0xf bank_mask:0xf bound_ctrl:1
	v_mul_f32_dpp v166, v166, v166 row_shr:4 row_mask:0xf bank_mask:0xf
	v_mul_f32_dpp v167, v167, v167 row_shr:4 row_mask:0xf bank_mask:0xf
	v_mul_f32_dpp v168, v168, v168 row_shr:4 row_mask:0xf bank_mask:0xf
	v_mul_f32_dpp v169, v169, v169 row_shr:4 row_mask:0xf bank_mask:0xf
	v_fmac_f32_dpp v204, v204, v166 row_shr:8 row_mask:0xf bank_mask:0xf bound_ctrl:1
	v_fmac_f32_dpp v205, v205, v167 row_shr:8 row_mask:0xf bank_mask:0xf bound_ctrl:1
	v_fmac_f32_dpp v206, v206, v168 row_shr:8 row_mask:0xf bank_mask:0xf bound_ctrl:1
	v_fmac_f32_dpp v207, v207, v169 row_shr:8 row_mask:0xf bank_mask:0xf bound_ctrl:1
	v_mul_f32_dpp v166, v166, v166 row_shr:8 row_mask:0xf bank_mask:0xf
	v_mul_f32_dpp v167, v167, v167 row_shr:8 row_mask:0xf bank_mask:0xf
	v_mul_f32_dpp v168, v168, v168 row_shr:8 row_mask:0xf bank_mask:0xf
	v_mul_f32_dpp v169, v169, v169 row_shr:8 row_mask:0xf bank_mask:0xf
	v_fma_f32 v208, v166, v20, v204
	v_fma_f32 v209, v167, v21, v205
	v_fma_f32 v210, v168, v22, v206
	v_fma_f32 v211, v169, v23, v207
	v_mov_b32_dpp v20, v208 row_newbcast:15 row_mask:0xf bank_mask:0xf
	v_mov_b32_dpp v21, v209 row_newbcast:15 row_mask:0xf bank_mask:0xf
	v_mov_b32_dpp v22, v210 row_newbcast:15 row_mask:0xf bank_mask:0xf
	v_mov_b32_dpp v23, v211 row_newbcast:15 row_mask:0xf bank_mask:0xf
	v_mul_f32_dpp v44, v166, v44 row_newbcast:15 row_mask:0xf bank_mask:0xf
	v_mul_f32_dpp v45, v167, v45 row_newbcast:15 row_mask:0xf bank_mask:0xf
	v_mul_f32_dpp v46, v168, v46 row_newbcast:15 row_mask:0xf bank_mask:0xf
	v_mul_f32_dpp v47, v169, v47 row_newbcast:15 row_mask:0xf bank_mask:0xf
	s_waitcnt lgkmcnt(0)
	s_waitcnt vmcnt(0)
	v_mov_b32_e32 v66, v82
	v_mov_b32_e32 v67, v83
	v_mov_b32_e32 v68, v84
	v_mov_b32_e32 v69, v85
	v_mov_b32_e32 v70, v86
	v_mov_b32_e32 v71, v87
	v_mov_b32_e32 v72, v88
	v_mov_b32_e32 v73, v89
	v_mov_b32_e32 v74, v90
	v_mov_b32_e32 v75, v91
	v_mov_b32_e32 v76, v92
	v_mov_b32_e32 v77, v93
	v_mov_b32_e32 v78, v94
	v_mov_b32_e32 v79, v95
	v_mov_b32_e32 v80, v96
	v_mov_b32_e32 v81, v97
	s_add_i32 s64, s64, 1
	s_cmp_lt_u32 s64, 3
	s_cbranch_scc1 .Lscan1_sub
	s_mov_b32 s62, 0x10001
	s_mov_b32 s63, 0x10001
	s_mov_b64 exec, s[62:63]
	s_add_u32 s62, s6, 0x204000
	s_addc_u32 s63, s7, 0
	global_store_dwordx4 v237, v[24:27], s[6:7] offset:0
	global_store_dwordx4 v237, v[0:3], s[62:63] offset:0
	global_store_dwordx4 v237, v[28:31], s[6:7] offset:64
	global_store_dwordx4 v237, v[4:7], s[62:63] offset:64
	global_store_dwordx4 v237, v[32:35], s[6:7] offset:128
	global_store_dwordx4 v237, v[8:11], s[62:63] offset:128
	global_store_dwordx4 v237, v[36:39], s[6:7] offset:192
	global_store_dwordx4 v237, v[12:15], s[62:63] offset:192
	global_store_dwordx4 v237, v[40:43], s[6:7] offset:256
	global_store_dwordx4 v237, v[16:19], s[62:63] offset:256
	global_store_dwordx4 v237, v[44:47], s[6:7] offset:320
	global_store_dwordx4 v237, v[20:23], s[62:63] offset:320
	s_mov_b64 exec, -1
	s_add_i32 s23, s23, s42

.Lscan2_back0:
	v_sqrt_f32_e32 v216, v216
	v_sqrt_f32_e32 v217, v217
	v_sqrt_f32_e32 v218, v218
	v_sqrt_f32_e32 v219, v219
	v_pk_mul_f32 v[204:205], v[204:205], v[216:217]
	v_pk_mul_f32 v[206:207], v[206:207], v[218:219]
	s_waitcnt lgkmcnt(0)
	v_mfma_f32_16x16x32_bf16 v[142:145], v[110:113], v[98:101], 0
	v_mfma_f32_16x16x32_bf16 v[146:149], v[122:125], v[98:101], 0
	v_mfma_f32_16x16x32_bf16 v[142:145], v[114:117], v[102:105], v[142:145]
	v_mfma_f32_16x16x32_bf16 v[146:149], v[126:129], v[102:105], v[146:149]
	v_mfma_f32_16x16x32_bf16 v[142:145], v[118:121], v[106:109], v[142:145]
	v_mfma_f32_16x16x32_bf16 v[146:149], v[130:133], v[106:109], v[146:149]
	s_nop 1
	v_fmac_f32_dpp v204, v204, v166 row_shr:1 row_mask:0xf bank_mask:0xf bound_ctrl:1
	v_fmac_f32_dpp v205, v205, v167 row_shr:1 row_mask:0xf bank_mask:0xf bound_ctrl:1
	v_fmac_f32_dpp v206, v206, v168 row_shr:1 row_mask:0xf bank_mask:0xf bound_ctrl:1
	v_fmac_f32_dpp v207, v207, v169 row_shr:1 row_mask:0xf bank_mask:0xf bound_ctrl:1
	v_mul_f32_dpp v166, v166, v166 row_shr:1 row_mask:0xf bank_mask:0xf
	v_mul_f32_dpp v167, v167, v167 row_shr:1 row_mask:0xf bank_mask:0xf
	v_mul_f32_dpp v168, v168, v168 row_shr:1 row_mask:0xf bank_mask:0xf
	v_mul_f32_dpp v169, v169, v169 row_shr:1 row_mask:0xf bank_mask:0xf
	v_fmac_f32_dpp v204, v204, v166 row_shr:2 row_mask:0xf bank_mask:0xf bound_ctrl:1
	v_fmac_f32_dpp v205, v205, v167 row_shr:2 row_mask:0xf bank_mask:0xf bound_ctrl:1
	v_fmac_f32_dpp v206, v206, v168 row_shr:2 row_mask:0xf bank_mask:0xf bound_ctrl:1
	v_fmac_f32_dpp v207, v207, v169 row_shr:2 row_mask:0xf bank_mask:0xf bound_ctrl:1
	v_mul_f32_dpp v166, v166, v166 row_shr:2 row_mask:0xf bank_mask:0xf
	v_mul_f32_dpp v167, v167, v167 row_shr:2 row_mask:0xf bank_mask:0xf
	v_mul_f32_dpp v168, v168, v168 row_shr:2 row_mask:0xf bank_mask:0xf
	v_mul_f32_dpp v169, v169, v169 row_shr:2 row_mask:0xf bank_mask:0xf
	v_fmac_f32_dpp v204, v204, v166 row_shr:4 row_mask:0xf bank_mask:0xf bound_ctrl:1
	v_fmac_f32_dpp v205, v205, v167 row_shr:4 row_mask:0xf bank_mask:0xf bound_ctrl:1
	v_fmac_f32_dpp v206, v206, v168 row_shr:4 row_mask:0xf bank_mask:0xf bound_ctrl:1
	v_fmac_f32_dpp v207, v207, v169 row_shr:4 row_mask:0xf bank_mask:0xf bound_ctrl:1
	v_mul_f32_dpp v166, v166, v166 row_shr:4 row_mask:0xf bank_mask:0xf
	v_mul_f32_dpp v167, v167, v167 row_shr:4 row_mask:0xf bank_mask:0xf
	v_mul_f32_dpp v168, v168, v168 row_shr:4 row_mask:0xf bank_mask:0xf
	v_mul_f32_dpp v169, v169, v169 row_shr:4 row_mask:0xf bank_mask:0xf
	v_fmac_f32_dpp v204, v204, v166 row_shr:8 row_mask:0xf bank_mask:0xf bound_ctrl:1
	v_fmac_f32_dpp v205, v205, v167 row_shr:8 row_mask:0xf bank_mask:0xf bound_ctrl:1
	v_fmac_f32_dpp v206, v206, v168 row_shr:8 row_mask:0xf bank_mask:0xf bound_ctrl:1
	v_fmac_f32_dpp v207, v207, v169 row_shr:8 row_mask:0xf bank_mask:0xf bound_ctrl:1
	v_mul_f32_dpp v166, v166, v166 row_shr:8 row_mask:0xf bank_mask:0xf
	v_mul_f32_dpp v167, v167, v167 row_shr:8 row_mask:0xf bank_mask:0xf
	v_mul_f32_dpp v168, v168, v168 row_shr:8 row_mask:0xf bank_mask:0xf
	v_mul_f32_dpp v169, v169, v169 row_shr:8 row_mask:0xf bank_mask:0xf
	v_fma_f32 v208, v166, v0, v204
	v_fma_f32 v209, v167, v1, v205
	v_fma_f32 v210, v168, v2, v206
	v_fma_f32 v211, v169, v3, v207
	v_mov_b32_dpp v0, v208 row_newbcast:15 row_mask:0xf bank_mask:0xf
	v_mov_b32_dpp v1, v209 row_newbcast:15 row_mask:0xf bank_mask:0xf
	v_mov_b32_dpp v2, v210 row_newbcast:15 row_mask:0xf bank_mask:0xf
	v_mov_b32_dpp v3, v211 row_newbcast:15 row_mask:0xf bank_mask:0xf
	s_waitcnt vmcnt(21)
	v_lshlrev_b32_e32 v212, 16, v24
	v_and_b32_e32 v213, 0xffff0000, v24
	v_lshlrev_b32_e32 v214, 16, v25
	v_and_b32_e32 v215, 0xffff0000, v25
	v_pk_mul_f32 v[216:217], v[212:213], v[212:213]
	v_pk_mul_f32 v[218:219], v[214:215], v[214:215]
	v_pk_fma_f32 v[216:217], v[216:217], v[36:37], v[36:37] op_sel:[0,0,1] op_sel_hi:[1,0,1]
	v_pk_fma_f32 v[218:219], v[218:219], v[36:37], v[36:37] op_sel:[0,0,1] op_sel_hi:[1,0,1]
	v_pk_mul_f32 v[216:217], v[212:213], v[216:217]
	v_pk_mul_f32 v[218:219], v[214:215], v[218:219]
	v_exp_f32_e32 v216, v216
	v_exp_f32_e32 v217, v217
	v_exp_f32_e32 v218, v218
	v_exp_f32_e32 v219, v219
	v_pk_add_f32 v[216:217], v[216:217], 1.0 op_sel_hi:[1,0]
	v_pk_add_f32 v[218:219], v[218:219], 1.0 op_sel_hi:[1,0]
	v_rcp_f32_e32 v216, v216
	v_rcp_f32_e32 v217, v217
	v_rcp_f32_e32 v218, v218
	v_rcp_f32_e32 v219, v219
	v_pk_mul_f32 v[216:217], v[212:213], v[216:217]
	v_pk_mul_f32 v[218:219], v[214:215], v[218:219]
	v_pk_mul_f32 v[216:217], v[216:217], v[208:209]
	v_pk_mul_f32 v[218:219], v[218:219], v[210:211]
	v_cvt_pk_bf16_f32 v242, v216, v217
	v_cvt_pk_bf16_f32 v243, v218, v219
	global_store_dwordx2 v236, v[242:243], s[100:101] offset:0
	ds_read_b128 v[110:113], v229 offset:6656
	ds_read_b128 v[122:125], v229 offset:26624
	ds_read_b128 v[114:117], v229 offset:6720
	ds_read_b128 v[126:129], v229 offset:26688
	ds_read_b128 v[118:121], v229 offset:6784
	ds_read_b128 v[130:133], v229 offset:26752
	v_pk_fma_f32 v[166:167], v[142:143], s[4:5], v[150:151] op_sel_hi:[1,0,1]
	v_pk_fma_f32 v[168:169], v[144:145], s[4:5], v[152:153] op_sel_hi:[1,0,1]
	v_pk_fma_f32 v[204:205], v[146:147], s[4:5], v[154:155] op_sel_hi:[1,0,1]
	v_pk_fma_f32 v[206:207], v[148:149], s[4:5], v[156:157] op_sel_hi:[1,0,1]
	v_exp_f32_e32 v166, v166
	v_exp_f32_e32 v167, v167
	v_exp_f32_e32 v168, v168
	v_exp_f32_e32 v169, v169
	v_exp_f32_e32 v204, v204
	v_exp_f32_e32 v205, v205
	v_exp_f32_e32 v206, v206
	v_exp_f32_e32 v207, v207
	v_pk_add_f32 v[166:167], v[166:167], 1.0 op_sel_hi:[1,0]
	v_pk_add_f32 v[168:169], v[168:169], 1.0 op_sel_hi:[1,0]
	v_pk_add_f32 v[204:205], v[204:205], 1.0 op_sel_hi:[1,0]
	v_pk_add_f32 v[206:207], v[206:207], 1.0 op_sel_hi:[1,0]
	v_rcp_f32_e32 v166, v166
	v_rcp_f32_e32 v167, v167
	v_rcp_f32_e32 v168, v168
	v_rcp_f32_e32 v169, v169
	v_rcp_f32_e32 v204, v204
	v_rcp_f32_e32 v205, v205
	v_rcp_f32_e32 v206, v206
	v_rcp_f32_e32 v207, v207
	v_pk_mul_f32 v[208:209], v[158:159], v[166:167]
	v_pk_mul_f32 v[210:211], v[160:161], v[168:169]
	v_pk_mul_f32 v[204:205], v[162:163], v[204:205]
	v_pk_mul_f32 v[206:207], v[164:165], v[206:207]
	ds_read_b128 v[150:153], v230 offset:128
	ds_read_b128 v[154:157], v230 offset:512
	ds_read_b128 v[158:161], v230 offset:896
	ds_read_b128 v[162:165], v231 offset:128
	v_exp_f32_e32 v166, v208
	v_exp_f32_e32 v167, v209
	v_exp_f32_e32 v168, v210
	v_exp_f32_e32 v169, v211
	v_pk_fma_f32 v[216:217], v[208:209], s[4:5], v[248:249] op_sel:[0,1,0] op_sel_hi:[1,1,0]
	v_pk_fma_f32 v[218:219], v[210:211], s[4:5], v[248:249] op_sel:[0,1,0] op_sel_hi:[1,1,0]
	v_pk_fma_f32 v[216:217], v[208:209], v[216:217], v[248:249] op_sel:[0,0,1] op_sel_hi:[1,1,1]
	v_pk_fma_f32 v[218:219], v[210:211], v[218:219], v[248:249] op_sel:[0,0,1] op_sel_hi:[1,1,1]
	v_min3_f32 v212, v208, v209, v210
	v_pk_fma_f32 v[216:217], v[208:209], v[216:217], v[250:251] op_sel_hi:[1,1,0]
	v_pk_fma_f32 v[218:219], v[210:211], v[218:219], v[250:251] op_sel_hi:[1,1,0]
	v_min_f32_e32 v212, v212, v211
	v_pk_fma_f32 v[216:217], v[208:209], v[216:217], v[250:251] op_sel:[0,0,1] op_sel_hi:[1,1,1]
	v_pk_fma_f32 v[218:219], v[210:211], v[218:219], v[250:251] op_sel:[0,0,1] op_sel_hi:[1,1,1]
	v_cmp_nlt_f32_e32 vcc, 0xbe38aa3b, v212
	v_pk_mul_f32 v[216:217], v[216:217], v[208:209]
	v_pk_mul_f32 v[218:219], v[218:219], v[210:211]
	s_cbranch_vccnz .Lscan2_far1
.Lscan2_back1:
	v_sqrt_f32_e32 v216, v216
	v_sqrt_f32_e32 v217, v217
	v_sqrt_f32_e32 v218, v218
	v_sqrt_f32_e32 v219, v219
	v_pk_mul_f32 v[204:205], v[204:205], v[216:217]
	v_pk_mul_f32 v[206:207], v[206:207], v[218:219]
	s_waitcnt lgkmcnt(0)
	v_mfma_f32_16x16x32_bf16 v[134:137], v[110:113], v[98:101], 0
	v_mfma_f32_16x16x32_bf16 v[138:141], v[122:125], v[98:101], 0
	v_mfma_f32_16x16x32_bf16 v[134:137], v[114:117], v[102:105], v[134:137]
	v_mfma_f32_16x16x32_bf16 v[138:141], v[126:129], v[102:105], v[138:141]
	v_mfma_f32_16x16x32_bf16 v[134:137], v[118:121], v[106:109], v[134:137]
	v_mfma_f32_16x16x32_bf16 v[138:141], v[130:133], v[106:109], v[138:141]
	s_nop 1
	v_fmac_f32_dpp v204, v204, v166 row_shr:1 row_mask:0xf bank_mask:0xf bound_ctrl:1
	v_fmac_f32_dpp v205, v205, v167 row_shr:1 row_mask:0xf bank_mask:0xf bound_ctrl:1
	v_fmac_f32_dpp v206, v206, v168 row_shr:1 row_mask:0xf bank_mask:0xf bound_ctrl:1
	v_fmac_f32_dpp v207, v207, v169 row_shr:1 row_mask:0xf bank_mask:0xf bound_ctrl:1
	v_mul_f32_dpp v166, v166, v166 row_shr:1 row_mask:0xf bank_mask:0xf
	v_mul_f32_dpp v167, v167, v167 row_shr:1 row_mask:0xf bank_mask:0xf
	v_mul_f32_dpp v168, v168, v168 row_shr:1 row_mask:0xf bank_mask:0xf
	v_mul_f32_dpp v169, v169, v169 row_shr:1 row_mask:0xf bank_mask:0xf
	v_fmac_f32_dpp v204, v204, v166 row_shr:2 row_mask:0xf bank_mask:0xf bound_ctrl:1
	v_fmac_f32_dpp v205, v205, v167 row_shr:2 row_mask:0xf bank_mask:0xf bound_ctrl:1
	v_fmac_f32_dpp v206, v206, v168 row_shr:2 row_mask:0xf bank_mask:0xf bound_ctrl:1
	v_fmac_f32_dpp v207, v207, v169 row_shr:2 row_mask:0xf bank_mask:0xf bound_ctrl:1
	v_mul_f32_dpp v166, v166, v166 row_shr:2 row_mask:0xf bank_mask:0xf
	v_mul_f32_dpp v167, v167, v167 row_shr:2 row_mask:0xf bank_mask:0xf
	v_mul_f32_dpp v168, v168, v168 row_shr:2 row_mask:0xf bank_mask:0xf
	v_mul_f32_dpp v169, v169, v169 row_shr:2 row_mask:0xf bank_mask:0xf
	v_fmac_f32_dpp v204, v204, v166 row_shr:4 row_mask:0xf bank_mask:0xf bound_ctrl:1
	v_fmac_f32_dpp v205, v205, v167 row_shr:4 row_mask:0xf bank_mask:0xf bound_ctrl:1
	v_fmac_f32_dpp v206, v206, v168 row_shr:4 row_mask:0xf bank_mask:0xf bound_ctrl:1
	v_fmac_f32_dpp v207, v207, v169 row_shr:4 row_mask:0xf bank_mask:0xf bound_ctrl:1
	v_mul_f32_dpp v166, v166, v166 row_shr:4 row_mask:0xf bank_mask:0xf
	v_mul_f32_dpp v167, v167, v167 row_shr:4 row_mask:0xf bank_mask:0xf
	v_mul_f32_dpp v168, v168, v168 row_shr:4 row_mask:0xf bank_mask:0xf
	v_mul_f32_dpp v169, v169, v169 row_shr:4 row_mask:0xf bank_mask:0xf
	v_fmac_f32_dpp v204, v204, v166 row_shr:8 row_mask:0xf bank_mask:0xf bound_ctrl:1
	v_fmac_f32_dpp v205, v205, v167 row_shr:8 row_mask:0xf bank_mask:0xf bound_ctrl:1
	v_fmac_f32_dpp v206, v206, v168 row_shr:8 row_mask:0xf bank_mask:0xf bound_ctrl:1
	v_fmac_f32_dpp v207, v207, v169 row_shr:8 row_mask:0xf bank_mask:0xf bound_ctrl:1
	v_mul_f32_dpp v166, v166, v166 row_shr:8 row_mask:0xf bank_mask:0xf
	v_mul_f32_dpp v167, v167, v167 row_shr:8 row_mask:0xf bank_mask:0xf
	v_mul_f32_dpp v168, v168, v168 row_shr:8 row_mask:0xf bank_mask:0xf
	v_mul_f32_dpp v169, v169, v169 row_shr:8 row_mask:0xf bank_mask:0xf
	v_fma_f32 v208, v166, v4, v204
	v_fma_f32 v209, v167, v5, v205
	v_fma_f32 v210, v168, v6, v206
	v_fma_f32 v211, v169, v7, v207
	v_mov_b32_dpp v4, v208 row_newbcast:15 row_mask:0xf bank_mask:0xf
	v_mov_b32_dpp v5, v209 row_newbcast:15 row_mask:0xf bank_mask:0xf
	v_mov_b32_dpp v6, v210 row_newbcast:15 row_mask:0xf bank_mask:0xf
	v_mov_b32_dpp v7, v211 row_newbcast:15 row_mask:0xf bank_mask:0xf
	s_waitcnt vmcnt(21)
	v_lshlrev_b32_e32 v212, 16, v26
	v_and_b32_e32 v213, 0xffff0000, v26
	v_lshlrev_b32_e32 v214, 16, v27
	v_and_b32_e32 v215, 0xffff0000, v27
	v_pk_mul_f32 v[216:217], v[212:213], v[212:213]
	v_pk_mul_f32 v[218:219], v[214:215], v[214:215]
	v_pk_fma_f32 v[216:217], v[216:217], v[36:37], v[36:37] op_sel:[0,0,1] op_sel_hi:[1,0,1]
	v_pk_fma_f32 v[218:219], v[218:219], v[36:37], v[36:37] op_sel:[0,0,1] op_sel_hi:[1,0,1]
	v_pk_mul_f32 v[216:217], v[212:213], v[216:217]
	v_pk_mul_f32 v[218:219], v[214:215], v[218:219]
	v_exp_f32_e32 v216, v216
	v_exp_f32_e32 v217, v217
	v_exp_f32_e32 v218, v218
	v_exp_f32_e32 v219, v219
	v_pk_add_f32 v[216:217], v[216:217], 1.0 op_sel_hi:[1,0]
	v_pk_add_f32 v[218:219], v[218:219], 1.0 op_sel_hi:[1,0]
	v_rcp_f32_e32 v216, v216
	v_rcp_f32_e32 v217, v217
	v_rcp_f32_e32 v218, v218
	v_rcp_f32_e32 v219, v219
	v_pk_mul_f32 v[216:217], v[212:213], v[216:217]
	v_pk_mul_f32 v[218:219], v[214:215], v[218:219]
	v_pk_mul_f32 v[216:217], v[216:217], v[208:209]
	v_pk_mul_f32 v[218:219], v[218:219], v[210:211]
	v_cvt_pk_bf16_f32 v242, v216, v217
	v_cvt_pk_bf16_f32 v243, v218, v219
	global_store_dwordx2 v236, v[242:243], s[100:101] offset:32
	ds_read_b128 v[110:113], v229 offset:9984
	ds_read_b128 v[122:125], v229 offset:29952
	ds_read_b128 v[114:117], v229 offset:10048
	ds_read_b128 v[126:129], v229 offset:30016
	ds_read_b128 v[118:121], v229 offset:10112
	ds_read_b128 v[130:133], v229 offset:30080
	v_pk_fma_f32 v[166:167], v[134:135], s[4:5], v[150:151] op_sel_hi:[1,0,1]
	v_pk_fma_f32 v[168:169], v[136:137], s[4:5], v[152:153] op_sel_hi:[1,0,1]
	v_pk_fma_f32 v[204:205], v[138:139], s[4:5], v[154:155] op_sel_hi:[1,0,1]
	v_pk_fma_f32 v[206:207], v[140:141], s[4:5], v[156:157] op_sel_hi:[1,0,1]
	v_exp_f32_e32 v166, v166
	v_exp_f32_e32 v167, v167
	v_exp_f32_e32 v168, v168
	v_exp_f32_e32 v169, v169
	v_exp_f32_e32 v204, v204
	v_exp_f32_e32 v205, v205
	v_exp_f32_e32 v206, v206
	v_exp_f32_e32 v207, v207
	v_pk_add_f32 v[166:167], v[166:167], 1.0 op_sel_hi:[1,0]
	v_pk_add_f32 v[168:169], v[168:169], 1.0 op_sel_hi:[1,0]
	v_pk_add_f32 v[204:205], v[204:205], 1.0 op_sel_hi:[1,0]
	v_pk_add_f32 v[206:207], v[206:207], 1.0 op_sel_hi:[1,0]
	v_rcp_f32_e32 v166, v166
	v_rcp_f32_e32 v167, v167
	v_rcp_f32_e32 v168, v168
	v_rcp_f32_e32 v169, v169
	v_rcp_f32_e32 v204, v204
	v_rcp_f32_e32 v205, v205
	v_rcp_f32_e32 v206, v206
	v_rcp_f32_e32 v207, v207
	v_pk_mul_f32 v[208:209], v[158:159], v[166:167]
	v_pk_mul_f32 v[210:211], v[160:161], v[168:169]
	v_pk_mul_f32 v[204:205], v[162:163], v[204:205]
	v_pk_mul_f32 v[206:207], v[164:165], v[206:207]
	ds_read_b128 v[150:153], v230 offset:192
	ds_read_b128 v[154:157], v230 offset:576
	ds_read_b128 v[158:161], v230 offset:960
	ds_read_b128 v[162:165], v231 offset:192
	v_exp_f32_e32 v166, v208
	v_exp_f32_e32 v167, v209
	v_exp_f32_e32 v168, v210
	v_exp_f32_e32 v169, v211
	v_pk_fma_f32 v[216:217], v[208:209], s[4:5], v[248:249] op_sel:[0,1,0] op_sel_hi:[1,1,0]
	v_pk_fma_f32 v[218:219], v[210:211], s[4:5], v[248:249] op_sel:[0,1,0] op_sel_hi:[1,1,0]
	v_pk_fma_f32 v[216:217], v[208:209], v[216:217], v[248:249] op_sel:[0,0,1] op_sel_hi:[1,1,1]
	v_pk_fma_f32 v[218:219], v[210:211], v[218:219], v[248:249] op_sel:[0,0,1] op_sel_hi:[1,1,1]
	v_min3_f32 v212, v208, v209, v210
	v_pk_fma_f32 v[216:217], v[208:209], v[216:217], v[250:251] op_sel_hi:[1,1,0]
	v_pk_fma_f32 v[218:219], v[210:211], v[218:219], v[250:251] op_sel_hi:[1,1,0]
	v_min_f32_e32 v212, v212, v211
	v_pk_fma_f32 v[216:217], v[208:209], v[216:217], v[250:251] op_sel:[0,0,1] op_sel_hi:[1,1,1]
	v_pk_fma_f32 v[218:219], v[210:211], v[218:219], v[250:251] op_sel:[0,0,1] op_sel_hi:[1,1,1]
	v_cmp_nlt_f32_e32 vcc, 0xbe38aa3b, v212
	v_pk_mul_f32 v[216:217], v[216:217], v[208:209]
	v_pk_mul_f32 v[218:219], v[218:219], v[210:211]
	s_cbranch_vccnz .Lscan2_far2
.Lscan2_back2:
	v_sqrt_f32_e32 v216, v216
	v_sqrt_f32_e32 v217, v217
	v_sqrt_f32_e32 v218, v218
	v_sqrt_f32_e32 v219, v219
	v_pk_mul_f32 v[204:205], v[204:205], v[216:217]
	v_pk_mul_f32 v[206:207], v[206:207], v[218:219]
	s_waitcnt lgkmcnt(0)
	v_mfma_f32_16x16x32_bf16 v[142:145], v[110:113], v[98:101], 0
	v_mfma_f32_16x16x32_bf16 v[146:149], v[122:125], v[98:101], 0
	v_mfma_f32_16x16x32_bf16 v[142:145], v[114:117], v[102:105], v[142:145]
	v_mfma_f32_16x16x32_bf16 v[146:149], v[126:129], v[102:105], v[146:149]
	v_mfma_f32_16x16x32_bf16 v[142:145], v[118:121], v[106:109], v[142:145]
	v_mfma_f32_16x16x32_bf16 v[146:149], v[130:133], v[106:109], v[146:149]
	s_nop 1
	v_fmac_f32_dpp v204, v204, v166 row_shr:1 row_mask:0xf bank_mask:0xf bound_ctrl:1
	v_fmac_f32_dpp v205, v205, v167 row_shr:1 row_mask:0xf bank_mask:0xf bound_ctrl:1
	v_fmac_f32_dpp v206, v206, v168 row_shr:1 row_mask:0xf bank_mask:0xf bound_ctrl:1
	v_fmac_f32_dpp v207, v207, v169 row_shr:1 row_mask:0xf bank_mask:0xf bound_ctrl:1
	v_mul_f32_dpp v166, v166, v166 row_shr:1 row_mask:0xf bank_mask:0xf
	v_mul_f32_dpp v167, v167, v167 row_shr:1 row_mask:0xf bank_mask:0xf
	v_mul_f32_dpp v168, v168, v168 row_shr:1 row_mask:0xf bank_mask:0xf
	v_mul_f32_dpp v169, v169, v169 row_shr:1 row_mask:0xf bank_mask:0xf
	v_fmac_f32_dpp v204, v204, v166 row_shr:2 row_mask:0xf bank_mask:0xf bound_ctrl:1
	v_fmac_f32_dpp v205, v205, v167 row_shr:2 row_mask:0xf bank_mask:0xf bound_ctrl:1
	v_fmac_f32_dpp v206, v206, v168 row_shr:2 row_mask:0xf bank_mask:0xf bound_ctrl:1
	v_fmac_f32_dpp v207, v207, v169 row_shr:2 row_mask:0xf bank_mask:0xf bound_ctrl:1
	v_mul_f32_dpp v166, v166, v166 row_shr:2 row_mask:0xf bank_mask:0xf
	v_mul_f32_dpp v167, v167, v167 row_shr:2 row_mask:0xf bank_mask:0xf
	v_mul_f32_dpp v168, v168, v168 row_shr:2 row_mask:0xf bank_mask:0xf
	v_mul_f32_dpp v169, v169, v169 row_shr:2 row_mask:0xf bank_mask:0xf
	v_fmac_f32_dpp v204, v204, v166 row_shr:4 row_mask:0xf bank_mask:0xf bound_ctrl:1
	v_fmac_f32_dpp v205, v205, v167 row_shr:4 row_mask:0xf bank_mask:0xf bound_ctrl:1
	v_fmac_f32_dpp v206, v206, v168 row_shr:4 row_mask:0xf bank_mask:0xf bound_ctrl:1
	v_fmac_f32_dpp v207, v207, v169 row_shr:4 row_mask:0xf bank_mask:0xf bound_ctrl:1
	v_mul_f32_dpp v166, v166, v166 row_shr:4 row_mask:0xf bank_mask:0xf
	v_mul_f32_dpp v167, v167, v167 row_shr:4 row_mask:0xf bank_mask:0xf
	v_mul_f32_dpp v168, v168, v168 row_shr:4 row_mask:0xf bank_mask:0xf
	v_mul_f32_dpp v169, v169, v169 row_shr:4 row_mask:0xf bank_mask:0xf
	v_fmac_f32_dpp v204, v204, v166 row_shr:8 row_mask:0xf bank_mask:0xf bound_ctrl:1
	v_fmac_f32_dpp v205, v205, v167 row_shr:8 row_mask:0xf bank_mask:0xf bound_ctrl:1
	v_fmac_f32_dpp v206, v206, v168 row_shr:8 row_mask:0xf bank_mask:0xf bound_ctrl:1
	v_fmac_f32_dpp v207, v207, v169 row_shr:8 row_mask:0xf bank_mask:0xf bound_ctrl:1
	v_mul_f32_dpp v166, v166, v166 row_shr:8 row_mask:0xf bank_mask:0xf
	v_mul_f32_dpp v167, v167, v167 row_shr:8 row_mask:0xf bank_mask:0xf
	v_mul_f32_dpp v168, v168, v168 row_shr:8 row_mask:0xf bank_mask:0xf
	v_mul_f32_dpp v169, v169, v169 row_shr:8 row_mask:0xf bank_mask:0xf
	v_fma_f32 v208, v166, v8, v204
	v_fma_f32 v209, v167, v9, v205
	v_fma_f32 v210, v168, v10, v206
	v_fma_f32 v211, v169, v11, v207
	v_mov_b32_dpp v8, v208 row_newbcast:15 row_mask:0xf bank_mask:0xf
	v_mov_b32_dpp v9, v209 row_newbcast:15 row_mask:0xf bank_mask:0xf
	v_mov_b32_dpp v10, v210 row_newbcast:15 row_mask:0xf bank_mask:0xf
	v_mov_b32_dpp v11, v211 row_newbcast:15 row_mask:0xf bank_mask:0xf
	s_waitcnt vmcnt(21)
	v_lshlrev_b32_e32 v212, 16, v28
	v_and_b32_e32 v213, 0xffff0000, v28
	v_lshlrev_b32_e32 v214, 16, v29
	v_and_b32_e32 v215, 0xffff0000, v29
	v_pk_mul_f32 v[216:217], v[212:213], v[212:213]
	v_pk_mul_f32 v[218:219], v[214:215], v[214:215]
	v_pk_fma_f32 v[216:217], v[216:217], v[36:37], v[36:37] op_sel:[0,0,1] op_sel_hi:[1,0,1]
	v_pk_fma_f32 v[218:219], v[218:219], v[36:37], v[36:37] op_sel:[0,0,1] op_sel_hi:[1,0,1]
	v_pk_mul_f32 v[216:217], v[212:213], v[216:217]
	v_pk_mul_f32 v[218:219], v[214:215], v[218:219]
	v_exp_f32_e32 v216, v216
	v_exp_f32_e32 v217, v217
	v_exp_f32_e32 v218, v218
	v_exp_f32_e32 v219, v219
	v_pk_add_f32 v[216:217], v[216:217], 1.0 op_sel_hi:[1,0]
	v_pk_add_f32 v[218:219], v[218:219], 1.0 op_sel_hi:[1,0]
	v_rcp_f32_e32 v216, v216
	v_rcp_f32_e32 v217, v217
	v_rcp_f32_e32 v218, v218
	v_rcp_f32_e32 v219, v219
	v_pk_mul_f32 v[216:217], v[212:213], v[216:217]
	v_pk_mul_f32 v[218:219], v[214:215], v[218:219]
	v_pk_mul_f32 v[216:217], v[216:217], v[208:209]
	v_pk_mul_f32 v[218:219], v[218:219], v[210:211]
	v_cvt_pk_bf16_f32 v242, v216, v217
	v_cvt_pk_bf16_f32 v243, v218, v219
	global_store_dwordx2 v236, v[242:243], s[100:101] offset:64
	ds_read_b128 v[110:113], v229 offset:13312
	ds_read_b128 v[122:125], v229 offset:33280
	ds_read_b128 v[114:117], v229 offset:13376
	ds_read_b128 v[126:129], v229 offset:33344
	ds_read_b128 v[118:121], v229 offset:13440
	ds_read_b128 v[130:133], v229 offset:33408
	v_pk_fma_f32 v[166:167], v[142:143], s[4:5], v[150:151] op_sel_hi:[1,0,1]
	v_pk_fma_f32 v[168:169], v[144:145], s[4:5], v[152:153] op_sel_hi:[1,0,1]
	v_pk_fma_f32 v[204:205], v[146:147], s[4:5], v[154:155] op_sel_hi:[1,0,1]
	v_pk_fma_f32 v[206:207], v[148:149], s[4:5], v[156:157] op_sel_hi:[1,0,1]
	v_exp_f32_e32 v166, v166
	v_exp_f32_e32 v167, v167
	v_exp_f32_e32 v168, v168
	v_exp_f32_e32 v169, v169
	v_exp_f32_e32 v204, v204
	v_exp_f32_e32 v205, v205
	v_exp_f32_e32 v206, v206
	v_exp_f32_e32 v207, v207
	v_pk_add_f32 v[166:167], v[166:167], 1.0 op_sel_hi:[1,0]
	v_pk_add_f32 v[168:169], v[168:169], 1.0 op_sel_hi:[1,0]
	v_pk_add_f32 v[204:205], v[204:205], 1.0 op_sel_hi:[1,0]
	v_pk_add_f32 v[206:207], v[206:207], 1.0 op_sel_hi:[1,0]
	v_rcp_f32_e32 v166, v166
	v_rcp_f32_e32 v167, v167
	v_rcp_f32_e32 v168, v168
	v_rcp_f32_e32 v169, v169
	v_rcp_f32_e32 v204, v204
	v_rcp_f32_e32 v205, v205
	v_rcp_f32_e32 v206, v206
	v_rcp_f32_e32 v207, v207
	v_pk_mul_f32 v[208:209], v[158:159], v[166:167]
	v_pk_mul_f32 v[210:211], v[160:161], v[168:169]
	v_pk_mul_f32 v[204:205], v[162:163], v[204:205]
	v_pk_mul_f32 v[206:207], v[164:165], v[206:207]
	ds_read_b128 v[150:153], v230 offset:256
	ds_read_b128 v[154:157], v230 offset:640
	ds_read_b128 v[158:161], v230 offset:1024
	ds_read_b128 v[162:165], v231 offset:256
	v_exp_f32_e32 v166, v208
	v_exp_f32_e32 v167, v209
	v_exp_f32_e32 v168, v210
	v_exp_f32_e32 v169, v211
	v_pk_fma_f32 v[216:217], v[208:209], s[4:5], v[248:249] op_sel:[0,1,0] op_sel_hi:[1,1,0]
	v_pk_fma_f32 v[218:219], v[210:211], s[4:5], v[248:249] op_sel:[0,1,0] op_sel_hi:[1,1,0]
	v_pk_fma_f32 v[216:217], v[208:209], v[216:217], v[248:249] op_sel:[0,0,1] op_sel_hi:[1,1,1]
	v_pk_fma_f32 v[218:219], v[210:211], v[218:219], v[248:249] op_sel:[0,0,1] op_sel_hi:[1,1,1]
	v_min3_f32 v212, v208, v209, v210
	v_pk_fma_f32 v[216:217], v[208:209], v[216:217], v[250:251] op_sel_hi:[1,1,0]
	v_pk_fma_f32 v[218:219], v[210:211], v[218:219], v[250:251] op_sel_hi:[1,1,0]
	v_min_f32_e32 v212, v212, v211
	v_pk_fma_f32 v[216:217], v[208:209], v[216:217], v[250:251] op_sel:[0,0,1] op_sel_hi:[1,1,1]
	v_pk_fma_f32 v[218:219], v[210:211], v[218:219], v[250:251] op_sel:[0,0,1] op_sel_hi:[1,1,1]
	v_cmp_nlt_f32_e32 vcc, 0xbe38aa3b, v212
	v_pk_mul_f32 v[216:217], v[216:217], v[208:209]
	v_pk_mul_f32 v[218:219], v[218:219], v[210:211]
	s_cbranch_vccnz .Lscan2_far3
.Lscan2_back3:
	v_sqrt_f32_e32 v216, v216
	v_sqrt_f32_e32 v217, v217
	v_sqrt_f32_e32 v218, v218
	v_sqrt_f32_e32 v219, v219
	v_pk_mul_f32 v[204:205], v[204:205], v[216:217]
	v_pk_mul_f32 v[206:207], v[206:207], v[218:219]
	s_waitcnt lgkmcnt(0)
	v_mfma_f32_16x16x32_bf16 v[134:137], v[110:113], v[98:101], 0
	v_mfma_f32_16x16x32_bf16 v[138:141], v[122:125], v[98:101], 0
	v_mfma_f32_16x16x32_bf16 v[134:137], v[114:117], v[102:105], v[134:137]
	v_mfma_f32_16x16x32_bf16 v[138:141], v[126:129], v[102:105], v[138:141]
	v_mfma_f32_16x16x32_bf16 v[134:137], v[118:121], v[106:109], v[134:137]
	v_mfma_f32_16x16x32_bf16 v[138:141], v[130:133], v[106:109], v[138:141]
	s_nop 1
	v_fmac_f32_dpp v204, v204, v166 row_shr:1 row_mask:0xf bank_mask:0xf bound_ctrl:1
	v_fmac_f32_dpp v205, v205, v167 row_shr:1 row_mask:0xf bank_mask:0xf bound_ctrl:1
	v_fmac_f32_dpp v206, v206, v168 row_shr:1 row_mask:0xf bank_mask:0xf bound_ctrl:1
	v_fmac_f32_dpp v207, v207, v169 row_shr:1 row_mask:0xf bank_mask:0xf bound_ctrl:1
	v_mul_f32_dpp v166, v166, v166 row_shr:1 row_mask:0xf bank_mask:0xf
	v_mul_f32_dpp v167, v167, v167 row_shr:1 row_mask:0xf bank_mask:0xf
	v_mul_f32_dpp v168, v168, v168 row_shr:1 row_mask:0xf bank_mask:0xf
	v_mul_f32_dpp v169, v169, v169 row_shr:1 row_mask:0xf bank_mask:0xf
	v_fmac_f32_dpp v204, v204, v166 row_shr:2 row_mask:0xf bank_mask:0xf bound_ctrl:1
	v_fmac_f32_dpp v205, v205, v167 row_shr:2 row_mask:0xf bank_mask:0xf bound_ctrl:1
	v_fmac_f32_dpp v206, v206, v168 row_shr:2 row_mask:0xf bank_mask:0xf bound_ctrl:1
	v_fmac_f32_dpp v207, v207, v169 row_shr:2 row_mask:0xf bank_mask:0xf bound_ctrl:1
	v_mul_f32_dpp v166, v166, v166 row_shr:2 row_mask:0xf bank_mask:0xf
	v_mul_f32_dpp v167, v167, v167 row_shr:2 row_mask:0xf bank_mask:0xf
	v_mul_f32_dpp v168, v168, v168 row_shr:2 row_mask:0xf bank_mask:0xf
	v_mul_f32_dpp v169, v169, v169 row_shr:2 row_mask:0xf bank_mask:0xf
	v_fmac_f32_dpp v204, v204, v166 row_shr:4 row_mask:0xf bank_mask:0xf bound_ctrl:1
	v_fmac_f32_dpp v205, v205, v167 row_shr:4 row_mask:0xf bank_mask:0xf bound_ctrl:1
	v_fmac_f32_dpp v206, v206, v168 row_shr:4 row_mask:0xf bank_mask:0xf bound_ctrl:1
	v_fmac_f32_dpp v207, v207, v169 row_shr:4 row_mask:0xf bank_mask:0xf bound_ctrl:1
	v_mul_f32_dpp v166, v166, v166 row_shr:4 row_mask:0xf bank_mask:0xf
	v_mul_f32_dpp v167, v167, v167 row_shr:4 row_mask:0xf bank_mask:0xf
	v_mul_f32_dpp v168, v168, v168 row_shr:4 row_mask:0xf bank_mask:0xf
	v_mul_f32_dpp v169, v169, v169 row_shr:4 row_mask:0xf bank_mask:0xf
	v_fmac_f32_dpp v204, v204, v166 row_shr:8 row_mask:0xf bank_mask:0xf bound_ctrl:1
	v_fmac_f32_dpp v205, v205, v167 row_shr:8 row_mask:0xf bank_mask:0xf bound_ctrl:1
	v_fmac_f32_dpp v206, v206, v168 row_shr:8 row_mask:0xf bank_mask:0xf bound_ctrl:1
	v_fmac_f32_dpp v207, v207, v169 row_shr:8 row_mask:0xf bank_mask:0xf bound_ctrl:1
	v_mul_f32_dpp v166, v166, v166 row_shr:8 row_mask:0xf bank_mask:0xf
	v_mul_f32_dpp v167, v167, v167 row_shr:8 row_mask:0xf bank_mask:0xf
	v_mul_f32_dpp v168, v168, v168 row_shr:8 row_mask:0xf bank_mask:0xf
	v_mul_f32_dpp v169, v169, v169 row_shr:8 row_mask:0xf bank_mask:0xf
	v_fma_f32 v208, v166, v12, v204
	v_fma_f32 v209, v167, v13, v205
	v_fma_f32 v210, v168, v14, v206
	v_fma_f32 v211, v169, v15, v207
	v_mov_b32_dpp v12, v208 row_newbcast:15 row_mask:0xf bank_mask:0xf
	v_mov_b32_dpp v13, v209 row_newbcast:15 row_mask:0xf bank_mask:0xf
	v_mov_b32_dpp v14, v210 row_newbcast:15 row_mask:0xf bank_mask:0xf
	v_mov_b32_dpp v15, v211 row_newbcast:15 row_mask:0xf bank_mask:0xf
	s_waitcnt vmcnt(21)
	v_lshlrev_b32_e32 v212, 16, v30
	v_and_b32_e32 v213, 0xffff0000, v30
	v_lshlrev_b32_e32 v214, 16, v31
	v_and_b32_e32 v215, 0xffff0000, v31
	v_pk_mul_f32 v[216:217], v[212:213], v[212:213]
	v_pk_mul_f32 v[218:219], v[214:215], v[214:215]
	v_pk_fma_f32 v[216:217], v[216:217], v[36:37], v[36:37] op_sel:[0,0,1] op_sel_hi:[1,0,1]
	v_pk_fma_f32 v[218:219], v[218:219], v[36:37], v[36:37] op_sel:[0,0,1] op_sel_hi:[1,0,1]
	v_pk_mul_f32 v[216:217], v[212:213], v[216:217]
	v_pk_mul_f32 v[218:219], v[214:215], v[218:219]
	v_exp_f32_e32 v216, v216
	v_exp_f32_e32 v217, v217
	v_exp_f32_e32 v218, v218
	v_exp_f32_e32 v219, v219
	v_pk_add_f32 v[216:217], v[216:217], 1.0 op_sel_hi:[1,0]
	v_pk_add_f32 v[218:219], v[218:219], 1.0 op_sel_hi:[1,0]
	v_rcp_f32_e32 v216, v216
	v_rcp_f32_e32 v217, v217
	v_rcp_f32_e32 v218, v218
	v_rcp_f32_e32 v219, v219
	v_pk_mul_f32 v[216:217], v[212:213], v[216:217]
	v_pk_mul_f32 v[218:219], v[214:215], v[218:219]
	v_pk_mul_f32 v[216:217], v[216:217], v[208:209]
	v_pk_mul_f32 v[218:219], v[218:219], v[210:211]
	v_cvt_pk_bf16_f32 v242, v216, v217
	v_cvt_pk_bf16_f32 v243, v218, v219
	global_store_dwordx2 v236, v[242:243], s[100:101] offset:96
	ds_read_b128 v[110:113], v229 offset:16640
	ds_read_b128 v[122:125], v229 offset:36608
	ds_read_b128 v[114:117], v229 offset:16704
	ds_read_b128 v[126:129], v229 offset:36672
	ds_read_b128 v[118:121], v229 offset:16768
	ds_read_b128 v[130:133], v229 offset:36736
	v_pk_fma_f32 v[166:167], v[134:135], s[4:5], v[150:151] op_sel_hi:[1,0,1]
	v_pk_fma_f32 v[168:169], v[136:137], s[4:5], v[152:153] op_sel_hi:[1,0,1]
	v_pk_fma_f32 v[204:205], v[138:139], s[4:5], v[154:155] op_sel_hi:[1,0,1]
	v_pk_fma_f32 v[206:207], v[140:141], s[4:5], v[156:157] op_sel_hi:[1,0,1]
	v_exp_f32_e32 v166, v166
	v_exp_f32_e32 v167, v167
	v_exp_f32_e32 v168, v168
	v_exp_f32_e32 v169, v169
	v_exp_f32_e32 v204, v204
	v_exp_f32_e32 v205, v205
	v_exp_f32_e32 v206, v206
	v_exp_f32_e32 v207, v207
	v_pk_add_f32 v[166:167], v[166:167], 1.0 op_sel_hi:[1,0]
	v_pk_add_f32 v[168:169], v[168:169], 1.0 op_sel_hi:[1,0]
	v_pk_add_f32 v[204:205], v[204:205], 1.0 op_sel_hi:[1,0]
	v_pk_add_f32 v[206:207], v[206:207], 1.0 op_sel_hi:[1,0]
	v_rcp_f32_e32 v166, v166
	v_rcp_f32_e32 v167, v167
	v_rcp_f32_e32 v168, v168
	v_rcp_f32_e32 v169, v169
	v_rcp_f32_e32 v204, v204
	v_rcp_f32_e32 v205, v205
	v_rcp_f32_e32 v206, v206
	v_rcp_f32_e32 v207, v207
	v_pk_mul_f32 v[208:209], v[158:159], v[166:167]
	v_pk_mul_f32 v[210:211], v[160:161], v[168:169]
	v_pk_mul_f32 v[204:205], v[162:163], v[204:205]
	v_pk_mul_f32 v[206:207], v[164:165], v[206:207]
	ds_read_b128 v[150:153], v230 offset:320
	ds_read_b128 v[154:157], v230 offset:704
	ds_read_b128 v[158:161], v230 offset:1088
	ds_read_b128 v[162:165], v231 offset:320
	v_exp_f32_e32 v166, v208
	v_exp_f32_e32 v167, v209
	v_exp_f32_e32 v168, v210
	v_exp_f32_e32 v169, v211
	v_pk_fma_f32 v[216:217], v[208:209], s[4:5], v[248:249] op_sel:[0,1,0] op_sel_hi:[1,1,0]
	v_pk_fma_f32 v[218:219], v[210:211], s[4:5], v[248:249] op_sel:[0,1,0] op_sel_hi:[1,1,0]
	v_pk_fma_f32 v[216:217], v[208:209], v[216:217], v[248:249] op_sel:[0,0,1] op_sel_hi:[1,1,1]
	v_pk_fma_f32 v[218:219], v[210:211], v[218:219], v[248:249] op_sel:[0,0,1] op_sel_hi:[1,1,1]
	v_min3_f32 v212, v208, v209, v210
	v_pk_fma_f32 v[216:217], v[208:209], v[216:217], v[250:251] op_sel_hi:[1,1,0]
	v_pk_fma_f32 v[218:219], v[210:211], v[218:219], v[250:251] op_sel_hi:[1,1,0]
	v_min_f32_e32 v212, v212, v211
	v_pk_fma_f32 v[216:217], v[208:209], v[216:217], v[250:251] op_sel:[0,0,1] op_sel_hi:[1,1,1]
	v_pk_fma_f32 v[218:219], v[210:211], v[218:219], v[250:251] op_sel:[0,0,1] op_sel_hi:[1,1,1]
	v_cmp_nlt_f32_e32 vcc, 0xbe38aa3b, v212
	v_pk_mul_f32 v[216:217], v[216:217], v[208:209]
	v_pk_mul_f32 v[218:219], v[218:219], v[210:211]
	s_cbranch_vccnz .Lscan2_far4
.Lscan2_back4:
	v_sqrt_f32_e32 v216, v216
	v_sqrt_f32_e32 v217, v217
	v_sqrt_f32_e32 v218, v218
	v_sqrt_f32_e32 v219, v219
	v_pk_mul_f32 v[204:205], v[204:205], v[216:217]
	v_pk_mul_f32 v[206:207], v[206:207], v[218:219]
	s_waitcnt lgkmcnt(0)
	v_mfma_f32_16x16x32_bf16 v[142:145], v[110:113], v[98:101], 0
	v_mfma_f32_16x16x32_bf16 v[146:149], v[122:125], v[98:101], 0
	v_mfma_f32_16x16x32_bf16 v[142:145], v[114:117], v[102:105], v[142:145]
	v_mfma_f32_16x16x32_bf16 v[146:149], v[126:129], v[102:105], v[146:149]
	v_mfma_f32_16x16x32_bf16 v[142:145], v[118:121], v[106:109], v[142:145]
	v_mfma_f32_16x16x32_bf16 v[146:149], v[130:133], v[106:109], v[146:149]
	s_nop 1
	v_fmac_f32_dpp v204, v204, v166 row_shr:1 row_mask:0xf bank_mask:0xf bound_ctrl:1
	v_fmac_f32_dpp v205, v205, v167 row_shr:1 row_mask:0xf bank_mask:0xf bound_ctrl:1
	v_fmac_f32_dpp v206, v206, v168 row_shr:1 row_mask:0xf bank_mask:0xf bound_ctrl:1
	v_fmac_f32_dpp v207, v207, v169 row_shr:1 row_mask:0xf bank_mask:0xf bound_ctrl:1
	v_mul_f32_dpp v166, v166, v166 row_shr:1 row_mask:0xf bank_mask:0xf
	v_mul_f32_dpp v167, v167, v167 row_shr:1 row_mask:0xf bank_mask:0xf
	v_mul_f32_dpp v168, v168, v168 row_shr:1 row_mask:0xf bank_mask:0xf
	v_mul_f32_dpp v169, v169, v169 row_shr:1 row_mask:0xf bank_mask:0xf
	v_fmac_f32_dpp v204, v204, v166 row_shr:2 row_mask:0xf bank_mask:0xf bound_ctrl:1
	v_fmac_f32_dpp v205, v205, v167 row_shr:2 row_mask:0xf bank_mask:0xf bound_ctrl:1
	v_fmac_f32_dpp v206, v206, v168 row_shr:2 row_mask:0xf bank_mask:0xf bound_ctrl:1
	v_fmac_f32_dpp v207, v207, v169 row_shr:2 row_mask:0xf bank_mask:0xf bound_ctrl:1
	v_mul_f32_dpp v166, v166, v166 row_shr:2 row_mask:0xf bank_mask:0xf
	v_mul_f32_dpp v167, v167, v167 row_shr:2 row_mask:0xf bank_mask:0xf
	v_mul_f32_dpp v168, v168, v168 row_shr:2 row_mask:0xf bank_mask:0xf
	v_mul_f32_dpp v169, v169, v169 row_shr:2 row_mask:0xf bank_mask:0xf
	v_fmac_f32_dpp v204, v204, v166 row_shr:4 row_mask:0xf bank_mask:0xf bound_ctrl:1
	v_fmac_f32_dpp v205, v205, v167 row_shr:4 row_mask:0xf bank_mask:0xf bound_ctrl:1
	v_fmac_f32_dpp v206, v206, v168 row_shr:4 row_mask:0xf bank_mask:0xf bound_ctrl:1
	v_fmac_f32_dpp v207, v207, v169 row_shr:4 row_mask:0xf bank_mask:0xf bound_ctrl:1
	v_mul_f32_dpp v166, v166, v166 row_shr:4 row_mask:0xf bank_mask:0xf
	v_mul_f32_dpp v167, v167, v167 row_shr:4 row_mask:0xf bank_mask:0xf
	v_mul_f32_dpp v168, v168, v168 row_shr:4 row_mask:0xf bank_mask:0xf
	v_mul_f32_dpp v169, v169, v169 row_shr:4 row_mask:0xf bank_mask:0xf
	v_fmac_f32_dpp v204, v204, v166 row_shr:8 row_mask:0xf bank_mask:0xf bound_ctrl:1
	v_fmac_f32_dpp v205, v205, v167 row_shr:8 row_mask:0xf bank_mask:0xf bound_ctrl:1
	v_fmac_f32_dpp v206, v206, v168 row_shr:8 row_mask:0xf bank_mask:0xf bound_ctrl:1
	v_fmac_f32_dpp v207, v207, v169 row_shr:8 row_mask:0xf bank_mask:0xf bound_ctrl:1
	v_mul_f32_dpp v166, v166, v166 row_shr:8 row_mask:0xf bank_mask:0xf
	v_mul_f32_dpp v167, v167, v167 row_shr:8 row_mask:0xf bank_mask:0xf
	v_mul_f32_dpp v168, v168, v168 row_shr:8 row_mask:0xf bank_mask:0xf
	v_mul_f32_dpp v169, v169, v169 row_shr:8 row_mask:0xf bank_mask:0xf
	v_fma_f32 v208, v166, v16, v204
	v_fma_f32 v209, v167, v17, v205
	v_fma_f32 v210, v168, v18, v206
	v_fma_f32 v211, v169, v19, v207
	v_mov_b32_dpp v16, v208 row_newbcast:15 row_mask:0xf bank_mask:0xf
	v_mov_b32_dpp v17, v209 row_newbcast:15 row_mask:0xf bank_mask:0xf
	v_mov_b32_dpp v18, v210 row_newbcast:15 row_mask:0xf bank_mask:0xf
	v_mov_b32_dpp v19, v211 row_newbcast:15 row_mask:0xf bank_mask:0xf
	s_waitcnt vmcnt(21)
	v_lshlrev_b32_e32 v212, 16, v32
	v_and_b32_e32 v213, 0xffff0000, v32
	v_lshlrev_b32_e32 v214, 16, v33
	v_and_b32_e32 v215, 0xffff0000, v33
	v_pk_mul_f32 v[216:217], v[212:213], v[212:213]
	v_pk_mul_f32 v[218:219], v[214:215], v[214:215]
	v_pk_fma_f32 v[216:217], v[216:217], v[36:37], v[36:37] op_sel:[0,0,1] op_sel_hi:[1,0,1]
	v_pk_fma_f32 v[218:219], v[218:219], v[36:37], v[36:37] op_sel:[0,0,1] op_sel_hi:[1,0,1]
	v_pk_mul_f32 v[216:217], v[212:213], v[216:217]
	v_pk_mul_f32 v[218:219], v[214:215], v[218:219]
	v_exp_f32_e32 v216, v216
	v_exp_f32_e32 v217, v217
	v_exp_f32_e32 v218, v218
	v_exp_f32_e32 v219, v219
	v_pk_add_f32 v[216:217], v[216:217], 1.0 op_sel_hi:[1,0]
	v_pk_add_f32 v[218:219], v[218:219], 1.0 op_sel_hi:[1,0]
	v_rcp_f32_e32 v216, v216
	v_rcp_f32_e32 v217, v217
	v_rcp_f32_e32 v218, v218
	v_rcp_f32_e32 v219, v219
	v_pk_mul_f32 v[216:217], v[212:213], v[216:217]
	v_pk_mul_f32 v[218:219], v[214:215], v[218:219]
	v_pk_mul_f32 v[216:217], v[216:217], v[208:209]
	v_pk_mul_f32 v[218:219], v[218:219], v[210:211]
	v_cvt_pk_bf16_f32 v242, v216, v217
	v_cvt_pk_bf16_f32 v243, v218, v219
	global_store_dwordx2 v236, v[242:243], s[100:101] offset:128
	v_pk_fma_f32 v[166:167], v[142:143], s[4:5], v[150:151] op_sel_hi:[1,0,1]
	v_pk_fma_f32 v[168:169], v[144:145], s[4:5], v[152:153] op_sel_hi:[1,0,1]
	v_pk_fma_f32 v[204:205], v[146:147], s[4:5], v[154:155] op_sel_hi:[1,0,1]
	v_pk_fma_f32 v[206:207], v[148:149], s[4:5], v[156:157] op_sel_hi:[1,0,1]
	v_exp_f32_e32 v166, v166
	v_exp_f32_e32 v167, v167
	v_exp_f32_e32 v168, v168
	v_exp_f32_e32 v169, v169
	v_exp_f32_e32 v204, v204
	v_exp_f32_e32 v205, v205
	v_exp_f32_e32 v206, v206
	v_exp_f32_e32 v207, v207
	v_pk_add_f32 v[166:167], v[166:167], 1.0 op_sel_hi:[1,0]
	v_pk_add_f32 v[168:169], v[168:169], 1.0 op_sel_hi:[1,0]
	v_pk_add_f32 v[204:205], v[204:205], 1.0 op_sel_hi:[1,0]
	v_pk_add_f32 v[206:207], v[206:207], 1.0 op_sel_hi:[1,0]
	v_rcp_f32_e32 v166, v166
	v_rcp_f32_e32 v167, v167
	v_rcp_f32_e32 v168, v168
	v_rcp_f32_e32 v169, v169
	v_rcp_f32_e32 v204, v204
	v_rcp_f32_e32 v205, v205
	v_rcp_f32_e32 v206, v206
	v_rcp_f32_e32 v207, v207
	v_pk_mul_f32 v[208:209], v[158:159], v[166:167]
	v_pk_mul_f32 v[210:211], v[160:161], v[168:169]
	v_pk_mul_f32 v[204:205], v[162:163], v[204:205]
	v_pk_mul_f32 v[206:207], v[164:165], v[206:207]
	v_exp_f32_e32 v166, v208
	v_exp_f32_e32 v167, v209
	v_exp_f32_e32 v168, v210
	v_exp_f32_e32 v169, v211
	v_pk_fma_f32 v[216:217], v[208:209], s[4:5], v[248:249] op_sel:[0,1,0] op_sel_hi:[1,1,0]
	v_pk_fma_f32 v[218:219], v[210:211], s[4:5], v[248:249] op_sel:[0,1,0] op_sel_hi:[1,1,0]
	v_pk_fma_f32 v[216:217], v[208:209], v[216:217], v[248:249] op_sel:[0,0,1] op_sel_hi:[1,1,1]
	v_pk_fma_f32 v[218:219], v[210:211], v[218:219], v[248:249] op_sel:[0,0,1] op_sel_hi:[1,1,1]
	v_min3_f32 v212, v208, v209, v210
	v_pk_fma_f32 v[216:217], v[208:209], v[216:217], v[250:251] op_sel_hi:[1,1,0]
	v_pk_fma_f32 v[218:219], v[210:211], v[218:219], v[250:251] op_sel_hi:[1,1,0]
	v_min_f32_e32 v212, v212, v211
	v_pk_fma_f32 v[216:217], v[208:209], v[216:217], v[250:251] op_sel:[0,0,1] op_sel_hi:[1,1,1]
	v_pk_fma_f32 v[218:219], v[210:211], v[218:219], v[250:251] op_sel:[0,0,1] op_sel_hi:[1,1,1]
	v_cmp_nlt_f32_e32 vcc, 0xbe38aa3b, v212
	v_pk_mul_f32 v[216:217], v[216:217], v[208:209]
	v_pk_mul_f32 v[218:219], v[218:219], v[210:211]
	s_cbranch_vccnz .Lscan2_far5
.Lscan2_back5:
	v_sqrt_f32_e32 v216, v216
	v_sqrt_f32_e32 v217, v217
	v_sqrt_f32_e32 v218, v218
	v_sqrt_f32_e32 v219, v219
	v_pk_mul_f32 v[204:205], v[204:205], v[216:217]
	v_pk_mul_f32 v[206:207], v[206:207], v[218:219]
	s_waitcnt lgkmcnt(0)
	s_nop 1
	v_fmac_f32_dpp v204, v204, v166 row_shr:1 row_mask:0xf bank_mask:0xf bound_ctrl:1
	v_fmac_f32_dpp v205, v205, v167 row_shr:1 row_mask:0xf bank_mask:0xf bound_ctrl:1
	v_fmac_f32_dpp v206, v206, v168 row_shr:1 row_mask:0xf bank_mask:0xf bound_ctrl:1
	v_fmac_f32_dpp v207, v207, v169 row_shr:1 row_mask:0xf bank_mask:0xf bound_ctrl:1
	v_mul_f32_dpp v166, v166, v166 row_shr:1 row_mask:0xf bank_mask:0xf
	v_mul_f32_dpp v167, v167, v167 row_shr:1 row_mask:0xf bank_mask:0xf
	v_mul_f32_dpp v168, v168, v168 row_shr:1 row_mask:0xf bank_mask:0xf
	v_mul_f32_dpp v169, v169, v169 row_shr:1 row_mask:0xf bank_mask:0xf
	v_fmac_f32_dpp v204, v204, v166 row_shr:2 row_mask:0xf bank_mask:0xf bound_ctrl:1
	v_fmac_f32_dpp v205, v205, v167 row_shr:2 row_mask:0xf bank_mask:0xf bound_ctrl:1
	v_fmac_f32_dpp v206, v206, v168 row_shr:2 row_mask:0xf bank_mask:0xf bound_ctrl:1
	v_fmac_f32_dpp v207, v207, v169 row_shr:2 row_mask:0xf bank_mask:0xf bound_ctrl:1
	v_mul_f32_dpp v166, v166, v166 row_shr:2 row_mask:0xf bank_mask:0xf
	v_mul_f32_dpp v167, v167, v167 row_shr:2 row_mask:0xf bank_mask:0xf
	v_mul_f32_dpp v168, v168, v168 row_shr:2 row_mask:0xf bank_mask:0xf
	v_mul_f32_dpp v169, v169, v169 row_shr:2 row_mask:0xf bank_mask:0xf
	v_fmac_f32_dpp v204, v204, v166 row_shr:4 row_mask:0xf bank_mask:0xf bound_ctrl:1
	v_fmac_f32_dpp v205, v205, v167 row_shr:4 row_mask:0xf bank_mask:0xf bound_ctrl:1
	v_fmac_f32_dpp v206, v206, v168 row_shr:4 row_mask:0xf bank_mask:0xf bound_ctrl:1
	v_fmac_f32_dpp v207, v207, v169 row_shr:4 row_mask:0xf bank_mask:0xf bound_ctrl:1
	v_mul_f32_dpp v166, v166, v166 row_shr:4 row_mask:0xf bank_mask:0xf
	v_mul_f32_dpp v167, v167, v167 row_shr:4 row_mask:0xf bank_mask:0xf
	v_mul_f32_dpp v168, v168, v168 row_shr:4 row_mask:0xf bank_mask:0xf
	v_mul_f32_dpp v169, v169, v169 row_shr:4 row_mask:0xf bank_mask:0xf
	v_fmac_f32_dpp v204, v204, v166 row_shr:8 row_mask:0xf bank_mask:0xf bound_ctrl:1
	v_fmac_f32_dpp v205, v205, v167 row_shr:8 row_mask:0xf bank_mask:0xf bound_ctrl:1
	v_fmac_f32_dpp v206, v206, v168 row_shr:8 row_mask:0xf bank_mask:0xf bound_ctrl:1
	v_fmac_f32_dpp v207, v207, v169 row_shr:8 row_mask:0xf bank_mask:0xf bound_ctrl:1
	v_mul_f32_dpp v166, v166, v166 row_shr:8 row_mask:0xf bank_mask:0xf
	v_mul_f32_dpp v167, v167, v167 row_shr:8 row_mask:0xf bank_mask:0xf
	v_mul_f32_dpp v168, v168, v168 row_shr:8 row_mask:0xf bank_mask:0xf
	v_mul_f32_dpp v169, v169, v169 row_shr:8 row_mask:0xf bank_mask:0xf
	v_fma_f32 v208, v166, v20, v204
	v_fma_f32 v209, v167, v21, v205
	v_fma_f32 v210, v168, v22, v206
	v_fma_f32 v211, v169, v23, v207
	v_mov_b32_dpp v20, v208 row_newbcast:15 row_mask:0xf bank_mask:0xf
	v_mov_b32_dpp v21, v209 row_newbcast:15 row_mask:0xf bank_mask:0xf
	v_mov_b32_dpp v22, v210 row_newbcast:15 row_mask:0xf bank_mask:0xf
	v_mov_b32_dpp v23, v211 row_newbcast:15 row_mask:0xf bank_mask:0xf
	s_waitcnt vmcnt(21)
	v_lshlrev_b32_e32 v212, 16, v34
	v_and_b32_e32 v213, 0xffff0000, v34
	v_lshlrev_b32_e32 v214, 16, v35
	v_and_b32_e32 v215, 0xffff0000, v35
	v_pk_mul_f32 v[216:217], v[212:213], v[212:213]
	v_pk_mul_f32 v[218:219], v[214:215], v[214:215]
	v_pk_fma_f32 v[216:217], v[216:217], v[36:37], v[36:37] op_sel:[0,0,1] op_sel_hi:[1,0,1]
	v_pk_fma_f32 v[218:219], v[218:219], v[36:37], v[36:37] op_sel:[0,0,1] op_sel_hi:[1,0,1]
	v_pk_mul_f32 v[216:217], v[212:213], v[216:217]
	v_pk_mul_f32 v[218:219], v[214:215], v[218:219]
	v_exp_f32_e32 v216, v216
	v_exp_f32_e32 v217, v217
	v_exp_f32_e32 v218, v218
	v_exp_f32_e32 v219, v219
	v_pk_add_f32 v[216:217], v[216:217], 1.0 op_sel_hi:[1,0]
	v_pk_add_f32 v[218:219], v[218:219], 1.0 op_sel_hi:[1,0]
	v_rcp_f32_e32 v216, v216
	v_rcp_f32_e32 v217, v217
	v_rcp_f32_e32 v218, v218
	v_rcp_f32_e32 v219, v219
	v_pk_mul_f32 v[216:217], v[212:213], v[216:217]
	v_pk_mul_f32 v[218:219], v[214:215], v[218:219]
	v_pk_mul_f32 v[216:217], v[216:217], v[208:209]
	v_pk_mul_f32 v[218:219], v[218:219], v[210:211]
	v_cvt_pk_bf16_f32 v242, v216, v217
	v_cvt_pk_bf16_f32 v243, v218, v219
	global_store_dwordx2 v236, v[242:243], s[100:101] offset:160
	s_waitcnt lgkmcnt(0)
	s_waitcnt vmcnt(6)
	v_mov_b32_e32 v66, v82
	v_mov_b32_e32 v67, v83
	v_mov_b32_e32 v68, v84
	v_mov_b32_e32 v69, v85
	v_mov_b32_e32 v70, v86
	v_mov_b32_e32 v71, v87
	v_mov_b32_e32 v72, v88
	v_mov_b32_e32 v73, v89
	v_mov_b32_e32 v74, v90
	v_mov_b32_e32 v75, v91
	v_mov_b32_e32 v76, v92
	v_mov_b32_e32 v77, v93
	v_mov_b32_e32 v78, v94
	v_mov_b32_e32 v79, v95
	v_mov_b32_e32 v80, v96
	v_mov_b32_e32 v81, v97
	s_add_u32 s6, s6, 0x18000
	s_addc_u32 s7, s7, 0
	s_add_u32 s100, s100, 0xc000
	s_addc_u32 s101, s101, 0
	s_add_i32 s64, s64, 1
	s_cmp_lt_u32 s64, 3
	s_cbranch_scc1 .Lscan2_sub
	s_add_i32 s23, s23, s42
